# conv loop address math simplified; gla_scan software-pipelined; gla_b in c1+c3 rewritten (loads batched, W in regs, pipelined LDS reads)
# speedup vs baseline: 1.0202x; 1.0202x over previous
; __device__ __forceinline__ float bf2f(bf16_t v) { return __uint_as_float(((unsigned)v) << 16); }
; __device__ __forceinline__ int ltid() { int t = threadIdx.x; asm volatile("" : "+v"(t)); return t; }
; __device__ __forceinline__ void gla_b(const Args& a, int l, int hd, int dir, int t0, unsigned char* sm, const bf16_t* __restrict__ PLR) {
;     ...
;     const float* w2 = a.in[18] + ((size_t)(l * 2 + dir) * 16) * 512 + hd * 128;
;     for (int i = tid; i < 2048; i += 512) W2s[i] = w2[(i >> 7) * 512 + (i & 127)];
;     if (tid < 128) Bs[tid] = a.in[19][(l * 2 + dir) * 512 + hd * 128 + tid];
;     for (int i = tid; i < 1024; i += 512) { const int j = i >> 4, r = i & 15; lrs[i] = bf2f(PLR[(size_t)(t0 + j) * 256 + dir * 16 + r]); }
;     __syncthreads();
; __device__ __forceinline__ void gla_load_vT(const bf16_t* __restrict__ PC, int hd, int t0, unsigned char* sm) {
;     ...
;     const int tid = ltid(), j = tid >> 3, v0 = (tid & 7) * 32;
;     const bf16_t* vp = PC + (size_t)(t0 + j) * 3072 + 1024 + hd * 256 + v0;
; #pragma unroll
;     for (int i = 0; i < 4; ++i) {
;         const u32x4 w = *(const u32x4*)(vp + i * 8);
;         const int b = v0 + i * 8;
;         vT[(b + 0) * 72 + j] = (bf16_t)(w.x & 0xffff); vT[(b + 1) * 72 + j] = (bf16_t)(w.x >> 16);
;         vT[(b + 2) * 72 + j] = (bf16_t)(w.y & 0xffff); vT[(b + 3) * 72 + j] = (bf16_t)(w.y >> 16);
;         vT[(b + 4) * 72 + j] = (bf16_t)(w.z & 0xffff); vT[(b + 5) * 72 + j] = (bf16_t)(w.z >> 16);
;         vT[(b + 6) * 72 + j] = (bf16_t)(w.w & 0xffff); vT[(b + 7) * 72 + j] = (bf16_t)(w.w >> 16);
.LBB0_223:
	s_lshl_b32 s0, s28, 6
	s_and_b32 s29, s0, 0x3fc0
	v_readlane_b32 s0, v246, 29
	v_readlane_b32 s1, v246, 30
	s_bfe_u32 s2, s28, 0x20008
	v_add_u32_e32 v0, s29, v122
	v_mov_b64_e32 v[8:9], s[0:1]
	s_movk_i32 s3, 0x1800
	v_mad_i64_i32 v[0:1], s[0:1], v0, s3, v[8:9]
	s_lshl_b32 s20, s2, 8
	v_lshl_add_u64 v[0:1], v[0:1], 0, s[20:21]
	v_lshl_add_u64 v[4:5], v[0:1], 0, v[64:65]
	v_mov_b32_e32 v10, v171
	global_load_dwordx4 v[0:3], v[4:5], off offset:1040
	s_nop 0
	global_load_dwordx4 v[4:7], v[4:5], off offset:1024
	s_lshl_b32 s20, s2, 9
	v_ashrrev_i32_e32 v28, 3, v10
	v_lshlrev_b32_e32 v10, 5, v10
	v_and_b32_e32 v29, 0xe0, v10
	v_add_u32_e32 v10, s29, v28
	v_mad_i64_i32 v[8:9], s[0:1], v10, s3, v[8:9]
	v_lshl_add_u64 v[8:9], v[8:9], 0, s[20:21]
	v_lshlrev_b32_e32 v10, 1, v29
	v_mov_b32_e32 v11, v65
	v_lshl_add_u64 v[8:9], v[8:9], 0, v[10:11]
	global_load_dwordx4 v[12:15], v[8:9], off offset:2048
	global_load_dwordx4 v[16:19], v[8:9], off offset:2064
	global_load_dwordx4 v[20:23], v[8:9], off offset:2080
	global_load_dwordx4 v[24:27], v[8:9], off offset:2096
	s_ashr_i32 s20, s28, 10
	v_readlane_b32 s0, v246, 35
	v_mul_u32_u24_e32 v9, 0x48, v29
	s_add_i32 s4, s20, s0
	v_lshlrev_b32_e32 v8, 1, v28
	v_lshlrev_b32_e32 v9, 1, v9
	v_readlane_b32 s0, v248, 20
	v_mov_b32_e32 v10, v171
	s_lshl_b32 s38, s2, 7
	v_add3_u32 v11, s0, v8, v9
	v_add3_u32 v8, s0, v9, v8
	s_movk_i32 s0, 0x800
	s_waitcnt vmcnt(0)
	ds_write_b16 v11, v12
	ds_write_b16_d16_hi v8, v12 offset:144
	ds_write_b16 v8, v13 offset:288
	ds_write_b16_d16_hi v8, v13 offset:432
	ds_write_b16 v8, v14 offset:576
	ds_write_b16_d16_hi v8, v14 offset:720
	ds_write_b16 v8, v15 offset:864
	ds_write_b16_d16_hi v8, v15 offset:1008
	s_waitcnt vmcnt(2)
	ds_write_b16 v11, v16 offset:1152
	ds_write_b16_d16_hi v8, v16 offset:1296
	ds_write_b16 v8, v17 offset:1440
	ds_write_b16_d16_hi v8, v17 offset:1584
	ds_write_b16 v8, v18 offset:1728
	ds_write_b16_d16_hi v8, v18 offset:1872
	ds_write_b16 v8, v19 offset:2016
	ds_write_b16_d16_hi v8, v19 offset:2160
	s_waitcnt vmcnt(1)
	ds_write_b16 v11, v20 offset:2304
	ds_write_b16_d16_hi v8, v20 offset:2448
	ds_write_b16 v8, v21 offset:2592
	ds_write_b16_d16_hi v8, v21 offset:2736
	ds_write_b16 v8, v22 offset:2880
	ds_write_b16_d16_hi v8, v22 offset:3024
	ds_write_b16 v8, v23 offset:3168
	ds_write_b16_d16_hi v8, v23 offset:3312
	s_waitcnt vmcnt(0)
	ds_write_b16 v11, v24 offset:3456
	ds_write_b16_d16_hi v8, v24 offset:3600
	ds_write_b16 v8, v25 offset:3744
	ds_write_b16_d16_hi v8, v25 offset:3888
	ds_write_b16 v8, v26 offset:4032
	ds_write_b16_d16_hi v8, v26 offset:4176
	ds_write_b16 v8, v27 offset:4320
	ds_write_b16_d16_hi v8, v27 offset:4464
	v_readlane_b32 s30, v247, 1
	v_readlane_b32 s31, v247, 2
	v_readlane_b32 s36, v247, 3
	v_readlane_b32 s37, v247, 4
	v_readlane_b32 s0, v246, 13
	v_readlane_b32 s1, v246, 14
	s_nop 3
	s_lshl_b32 s2, s4, 15
	s_add_u32 s30, s30, s2
	s_addc_u32 s31, s31, 0
	s_lshl_b32 s2, s38, 2
	s_add_u32 s30, s30, s2
	s_addc_u32 s31, s31, 0
	s_lshl_b32 s2, s4, 9
	s_or_b32 s2, s2, s38
	s_lshl_b32 s2, s2, 2
	s_add_u32 s36, s36, s2
	s_addc_u32 s37, s37, 0
	s_lshl_b32 s2, s20, 5
	s_add_u32 s0, s0, s2
	s_addc_u32 s1, s1, 0
	s_lshl_b32 s2, s29, 9
	s_add_u32 s0, s0, s2
	s_addc_u32 s1, s1, 0
	v_and_b32_e32 v8, 0x7f, v171
	v_lshlrev_b32_e32 v8, 2, v8
	v_lshlrev_b32_e32 v9, 2, v171
	v_lshrrev_b32_e32 v10, 4, v171
	v_lshlrev_b32_e32 v10, 9, v10
	v_and_b32_e32 v11, 15, v171
	v_lshl_or_b32 v10, v11, 1, v10
	v_add_u32_e32 v11, 0x4000, v10
	global_load_ushort v12, v10, s[0:1]
	global_load_ushort v13, v11, s[0:1]
	global_load_dword v14, v8, s[36:37]
	global_load_dword v201, v8, s[30:31]
	global_load_dword v202, v8, s[30:31] offset:2048
	s_add_u32 s30, s30, 0x1000
	s_addc_u32 s31, s31, 0
	global_load_dword v203, v8, s[30:31]
	global_load_dword v204, v8, s[30:31] offset:2048
	s_add_u32 s30, s30, 0x1000
	s_addc_u32 s31, s31, 0
	global_load_dword v205, v8, s[30:31]
	global_load_dword v206, v8, s[30:31] offset:2048
	s_add_u32 s30, s30, 0x1000
	s_addc_u32 s31, s31, 0
	global_load_dword v207, v8, s[30:31]
	global_load_dword v208, v8, s[30:31] offset:2048
	s_add_u32 s30, s30, 0x1000
	s_addc_u32 s31, s31, 0
	global_load_dword v209, v8, s[30:31]
	global_load_dword v210, v8, s[30:31] offset:2048
	s_add_u32 s30, s30, 0x1000
	s_addc_u32 s31, s31, 0
	global_load_dword v211, v8, s[30:31]
	global_load_dword v212, v8, s[30:31] offset:2048
	s_add_u32 s30, s30, 0x1000
	s_addc_u32 s31, s31, 0
	global_load_dword v213, v8, s[30:31]
	global_load_dword v214, v8, s[30:31] offset:2048
	s_add_u32 s30, s30, 0x1000
	s_addc_u32 s31, s31, 0
	global_load_dword v215, v8, s[30:31]
	global_load_dword v216, v8, s[30:31] offset:2048
	s_waitcnt vmcnt(17)
	v_lshlrev_b32_e32 v12, 16, v12
	v_lshlrev_b32_e32 v13, 16, v13
	ds_write_b32 v9, v12 offset:41728
	ds_write_b32 v9, v13 offset:43776
	s_waitcnt lgkmcnt(0)
	s_barrier
; __device__ __forceinline__ void gla_b(const Args& a, int l, int hd, int dir, int t0, unsigned char* sm, const bf16_t* __restrict__ PLR) {
;     ...
;     const int d = tid & 127, q = tid >> 7;
;     float run = 0.f;
;     for (int k = 0; k < 16; ++k) {
;         const int s = q * 16 + k, j = dir ? 63 - s : s;
;         float x = Bs[d];
; #pragma unroll
;         for (int r = 0; r < 16; ++r) x += lrs[j * 16 + r] * W2s[r * 128 + d];
;         const float g = (fminf(x, 0.f) - __logf(1.f + __expf(-fabsf(x)))) * (1.f / 16.f);
;         run += g; Gb[j * 129 + d] = run;
;     }
	v_lshrrev_b32_e32 v15, 7, v171
	v_lshlrev_b32_e32 v15, 4, v15
	v_sub_u32_e32 v16, 63, v15
	s_cmpk_lt_u32 s28, 0x400
	s_cselect_b64 s[0:1], -1, 0
	s_cselect_b32 s3, 64, 0xffffffc0
	s_movk_i32 s101, 0x204
	s_cselect_b32 s101, s101, 0xfffffdfc
	v_cndmask_b32_e64 v15, v16, v15, s[0:1]
	v_lshlrev_b32_e32 v27, 6, v15
	v_add_u32_e32 v27, 0xa300, v27
	v_add_u32_e32 v28, s3, v27
	v_mul_u32_u24_e32 v16, 0x204, v15
	v_add_u32_e32 v16, v16, v8
	s_lshl_b32 s100, s3, 1
	ds_read_b128 v[172:175], v27
	ds_read_b128 v[176:179], v27 offset:16
	ds_read_b128 v[180:183], v27 offset:32
	ds_read_b128 v[164:167], v27 offset:48
	ds_read_b128 v[228:231], v28
	ds_read_b128 v[232:235], v28 offset:16
	ds_read_b128 v[236:239], v28 offset:32
	ds_read_b128 v[240:243], v28 offset:48
	s_mov_b32 s2, 0x3d800000
	s_waitcnt vmcnt(0)
	s_waitcnt lgkmcnt(0)
	v_mov_b32_e32 v25, v14
	v_mov_b32_e32 v26, v14
	v_fmac_f32_e32 v25, v172, v201
	v_fmac_f32_e32 v26, v228, v201
	v_fmac_f32_e32 v25, v173, v202
	v_fmac_f32_e32 v26, v229, v202
	v_fmac_f32_e32 v25, v174, v203
	v_fmac_f32_e32 v26, v230, v203
	v_fmac_f32_e32 v25, v175, v204
	v_fmac_f32_e32 v26, v231, v204
	v_fmac_f32_e32 v25, v176, v205
	v_fmac_f32_e32 v26, v232, v205
	v_fmac_f32_e32 v25, v177, v206
	v_fmac_f32_e32 v26, v233, v206
	v_fmac_f32_e32 v25, v178, v207
	v_fmac_f32_e32 v26, v234, v207
	v_fmac_f32_e32 v25, v179, v208
	v_fmac_f32_e32 v26, v235, v208
	v_fmac_f32_e32 v25, v180, v209
	v_fmac_f32_e32 v26, v236, v209
	v_fmac_f32_e32 v25, v181, v210
	v_fmac_f32_e32 v26, v237, v210
	v_fmac_f32_e32 v25, v182, v211
	v_fmac_f32_e32 v26, v238, v211
	v_fmac_f32_e32 v25, v183, v212
	v_fmac_f32_e32 v26, v239, v212
	v_fmac_f32_e32 v25, v164, v213
	v_fmac_f32_e32 v26, v240, v213
	v_fmac_f32_e32 v25, v165, v214
	v_fmac_f32_e32 v26, v241, v214
	v_fmac_f32_e32 v25, v166, v215
	v_fmac_f32_e32 v26, v242, v215
	v_fmac_f32_e32 v25, v167, v216
	v_fmac_f32_e32 v26, v243, v216
	v_add_u32_e32 v27, s100, v27
	v_add_u32_e32 v28, s100, v28
	ds_read_b128 v[172:175], v27
	ds_read_b128 v[176:179], v27 offset:16
	ds_read_b128 v[180:183], v27 offset:32
	ds_read_b128 v[164:167], v27 offset:48
	ds_read_b128 v[228:231], v28
	ds_read_b128 v[232:235], v28 offset:16
	ds_read_b128 v[236:239], v28 offset:32
	ds_read_b128 v[240:243], v28 offset:48
	v_mul_f32_e64 v17, |v25|, s61
	v_mul_f32_e64 v18, |v26|, s61
	v_exp_f32_e32 v17, v17
	v_exp_f32_e32 v18, v18
	v_min_f32_e32 v19, 0, v25
	v_min_f32_e32 v20, 0, v26
	v_add_f32_e32 v17, 1.0, v17
	v_add_f32_e32 v18, 1.0, v18
	v_cmp_gt_f32_e64 s[4:5], s24, v17
	v_cmp_gt_f32_e64 s[6:7], s24, v18
	s_nop 1
	v_cndmask_b32_e64 v21, 0, 32, s[4:5]
	v_cndmask_b32_e64 v22, 0, 32, s[6:7]
	v_ldexp_f32 v17, v17, v21
	v_ldexp_f32 v18, v18, v22
	v_log_f32_e32 v17, v17
	v_log_f32_e32 v18, v18
	v_cndmask_b32_e64 v21, 0, v192, s[4:5]
	v_cndmask_b32_e64 v22, 0, v192, s[6:7]
	v_mul_f32_e32 v23, 0x3f317217, v17
	v_mul_f32_e32 v24, 0x3f317217, v18
	v_fma_f32 v23, v17, s62, -v23
	v_fma_f32 v24, v18, s62, -v24
	v_fmac_f32_e32 v23, 0x3377d1cf, v17
	v_fmac_f32_e32 v24, 0x3377d1cf, v18
	v_fmac_f32_e32 v23, 0x3f317217, v17
	v_fmac_f32_e32 v24, 0x3f317217, v18
	v_cmp_lt_f32_e64 s[30:31], |v17|, s63
	v_cmp_lt_f32_e64 s[36:37], |v18|, s63
	s_nop 1
	v_cndmask_b32_e64 v17, v17, v23, s[30:31]
	v_cndmask_b32_e64 v18, v18, v24, s[36:37]
	v_sub_f32_e32 v17, v17, v21
	v_sub_f32_e32 v18, v18, v22
	v_sub_f32_e32 v17, v19, v17
	v_sub_f32_e32 v18, v20, v18
	v_fma_f32 v217, v17, s2, v65
	v_fma_f32 v218, v18, s2, v217
	s_waitcnt lgkmcnt(0)
	v_mov_b32_e32 v25, v14
	v_mov_b32_e32 v26, v14
	v_fmac_f32_e32 v25, v172, v201
	v_fmac_f32_e32 v26, v228, v201
	v_fmac_f32_e32 v25, v173, v202
	v_fmac_f32_e32 v26, v229, v202
	v_fmac_f32_e32 v25, v174, v203
	v_fmac_f32_e32 v26, v230, v203
	v_fmac_f32_e32 v25, v175, v204
	v_fmac_f32_e32 v26, v231, v204
	v_fmac_f32_e32 v25, v176, v205
	v_fmac_f32_e32 v26, v232, v205
	v_fmac_f32_e32 v25, v177, v206
	v_fmac_f32_e32 v26, v233, v206
	v_fmac_f32_e32 v25, v178, v207
	v_fmac_f32_e32 v26, v234, v207
	v_fmac_f32_e32 v25, v179, v208
	v_fmac_f32_e32 v26, v235, v208
	v_fmac_f32_e32 v25, v180, v209
	v_fmac_f32_e32 v26, v236, v209
	v_fmac_f32_e32 v25, v181, v210
	v_fmac_f32_e32 v26, v237, v210
	v_fmac_f32_e32 v25, v182, v211
	v_fmac_f32_e32 v26, v238, v211
	v_fmac_f32_e32 v25, v183, v212
	v_fmac_f32_e32 v26, v239, v212
	v_fmac_f32_e32 v25, v164, v213
	v_fmac_f32_e32 v26, v240, v213
	v_fmac_f32_e32 v25, v165, v214
	v_fmac_f32_e32 v26, v241, v214
	v_fmac_f32_e32 v25, v166, v215
	v_fmac_f32_e32 v26, v242, v215
	v_fmac_f32_e32 v25, v167, v216
	v_fmac_f32_e32 v26, v243, v216
	v_add_u32_e32 v27, s100, v27
	v_add_u32_e32 v28, s100, v28
	ds_read_b128 v[172:175], v27
	ds_read_b128 v[176:179], v27 offset:16
	ds_read_b128 v[180:183], v27 offset:32
	ds_read_b128 v[164:167], v27 offset:48
	ds_read_b128 v[228:231], v28
	ds_read_b128 v[232:235], v28 offset:16
	ds_read_b128 v[236:239], v28 offset:32
	ds_read_b128 v[240:243], v28 offset:48
	v_mul_f32_e64 v17, |v25|, s61
	v_mul_f32_e64 v18, |v26|, s61
	v_exp_f32_e32 v17, v17
	v_exp_f32_e32 v18, v18
	v_min_f32_e32 v19, 0, v25
	v_min_f32_e32 v20, 0, v26
	v_add_f32_e32 v17, 1.0, v17
	v_add_f32_e32 v18, 1.0, v18
	v_cmp_gt_f32_e64 s[4:5], s24, v17
	v_cmp_gt_f32_e64 s[6:7], s24, v18
	s_nop 1
	v_cndmask_b32_e64 v21, 0, 32, s[4:5]
	v_cndmask_b32_e64 v22, 0, 32, s[6:7]
	v_ldexp_f32 v17, v17, v21
	v_ldexp_f32 v18, v18, v22
	v_log_f32_e32 v17, v17
	v_log_f32_e32 v18, v18
	v_cndmask_b32_e64 v21, 0, v192, s[4:5]
	v_cndmask_b32_e64 v22, 0, v192, s[6:7]
	v_mul_f32_e32 v23, 0x3f317217, v17
	v_mul_f32_e32 v24, 0x3f317217, v18
	v_fma_f32 v23, v17, s62, -v23
	v_fma_f32 v24, v18, s62, -v24
	v_fmac_f32_e32 v23, 0x3377d1cf, v17
	v_fmac_f32_e32 v24, 0x3377d1cf, v18
	v_fmac_f32_e32 v23, 0x3f317217, v17
	v_fmac_f32_e32 v24, 0x3f317217, v18
	v_cmp_lt_f32_e64 s[30:31], |v17|, s63
	v_cmp_lt_f32_e64 s[36:37], |v18|, s63
	s_nop 1
	v_cndmask_b32_e64 v17, v17, v23, s[30:31]
	v_cndmask_b32_e64 v18, v18, v24, s[36:37]
	v_sub_f32_e32 v17, v17, v21
	v_sub_f32_e32 v18, v18, v22
	v_sub_f32_e32 v17, v19, v17
	v_sub_f32_e32 v18, v20, v18
	v_fma_f32 v219, v17, s2, v218
	v_fma_f32 v220, v18, s2, v219
	s_waitcnt lgkmcnt(0)
; __device__ __forceinline__ void gla_b(const Args& a, int l, int hd, int dir, int t0, unsigned char* sm, const bf16_t* __restrict__ PLR) {
;     ...
;     for (int k = 0; k < 16; ++k) {
;         const int s = q * 16 + k, j = dir ? 63 - s : s;
;         float x = Bs[d];
; #pragma unroll
;         for (int r = 0; r < 16; ++r) x += lrs[j * 16 + r] * W2s[r * 128 + d];
;         const float g = (fminf(x, 0.f) - __logf(1.f + __expf(-fabsf(x)))) * (1.f / 16.f);
;         run += g; Gb[j * 129 + d] = run;
;     }
	v_mov_b32_e32 v25, v14
	v_mov_b32_e32 v26, v14
	v_fmac_f32_e32 v25, v172, v201
	v_fmac_f32_e32 v26, v228, v201
	v_fmac_f32_e32 v25, v173, v202
	v_fmac_f32_e32 v26, v229, v202
	v_fmac_f32_e32 v25, v174, v203
	v_fmac_f32_e32 v26, v230, v203
	v_fmac_f32_e32 v25, v175, v204
	v_fmac_f32_e32 v26, v231, v204
	v_fmac_f32_e32 v25, v176, v205
	v_fmac_f32_e32 v26, v232, v205
	v_fmac_f32_e32 v25, v177, v206
	v_fmac_f32_e32 v26, v233, v206
	v_fmac_f32_e32 v25, v178, v207
	v_fmac_f32_e32 v26, v234, v207
	v_fmac_f32_e32 v25, v179, v208
	v_fmac_f32_e32 v26, v235, v208
	v_fmac_f32_e32 v25, v180, v209
	v_fmac_f32_e32 v26, v236, v209
	v_fmac_f32_e32 v25, v181, v210
	v_fmac_f32_e32 v26, v237, v210
	v_fmac_f32_e32 v25, v182, v211
	v_fmac_f32_e32 v26, v238, v211
	v_fmac_f32_e32 v25, v183, v212
	v_fmac_f32_e32 v26, v239, v212
	v_fmac_f32_e32 v25, v164, v213
	v_fmac_f32_e32 v26, v240, v213
	v_fmac_f32_e32 v25, v165, v214
	v_fmac_f32_e32 v26, v241, v214
	v_fmac_f32_e32 v25, v166, v215
	v_fmac_f32_e32 v26, v242, v215
	v_fmac_f32_e32 v25, v167, v216
	v_fmac_f32_e32 v26, v243, v216
	v_add_u32_e32 v27, s100, v27
	v_add_u32_e32 v28, s100, v28
	ds_read_b128 v[172:175], v27
	ds_read_b128 v[176:179], v27 offset:16
	ds_read_b128 v[180:183], v27 offset:32
	ds_read_b128 v[164:167], v27 offset:48
	ds_read_b128 v[228:231], v28
	ds_read_b128 v[232:235], v28 offset:16
	ds_read_b128 v[236:239], v28 offset:32
	ds_read_b128 v[240:243], v28 offset:48
	v_mul_f32_e64 v17, |v25|, s61
	v_mul_f32_e64 v18, |v26|, s61
	v_exp_f32_e32 v17, v17
	v_exp_f32_e32 v18, v18
	v_min_f32_e32 v19, 0, v25
	v_min_f32_e32 v20, 0, v26
	v_add_f32_e32 v17, 1.0, v17
	v_add_f32_e32 v18, 1.0, v18
	v_cmp_gt_f32_e64 s[4:5], s24, v17
	v_cmp_gt_f32_e64 s[6:7], s24, v18
	s_nop 1
	v_cndmask_b32_e64 v21, 0, 32, s[4:5]
	v_cndmask_b32_e64 v22, 0, 32, s[6:7]
	v_ldexp_f32 v17, v17, v21
	v_ldexp_f32 v18, v18, v22
	v_log_f32_e32 v17, v17
	v_log_f32_e32 v18, v18
	v_cndmask_b32_e64 v21, 0, v192, s[4:5]
	v_cndmask_b32_e64 v22, 0, v192, s[6:7]
	v_mul_f32_e32 v23, 0x3f317217, v17
	v_mul_f32_e32 v24, 0x3f317217, v18
	v_fma_f32 v23, v17, s62, -v23
	v_fma_f32 v24, v18, s62, -v24
	v_fmac_f32_e32 v23, 0x3377d1cf, v17
	v_fmac_f32_e32 v24, 0x3377d1cf, v18
	v_fmac_f32_e32 v23, 0x3f317217, v17
	v_fmac_f32_e32 v24, 0x3f317217, v18
	v_cmp_lt_f32_e64 s[30:31], |v17|, s63
	v_cmp_lt_f32_e64 s[36:37], |v18|, s63
	s_nop 1
	v_cndmask_b32_e64 v17, v17, v23, s[30:31]
	v_cndmask_b32_e64 v18, v18, v24, s[36:37]
	v_sub_f32_e32 v17, v17, v21
	v_sub_f32_e32 v18, v18, v22
	v_sub_f32_e32 v17, v19, v17
	v_sub_f32_e32 v18, v20, v18
	v_fma_f32 v221, v17, s2, v220
	v_fma_f32 v222, v18, s2, v221
	s_waitcnt lgkmcnt(0)
	v_mov_b32_e32 v25, v14
	v_mov_b32_e32 v26, v14
	v_fmac_f32_e32 v25, v172, v201
	v_fmac_f32_e32 v26, v228, v201
	v_fmac_f32_e32 v25, v173, v202
	v_fmac_f32_e32 v26, v229, v202
	v_fmac_f32_e32 v25, v174, v203
	v_fmac_f32_e32 v26, v230, v203
	v_fmac_f32_e32 v25, v175, v204
	v_fmac_f32_e32 v26, v231, v204
	v_fmac_f32_e32 v25, v176, v205
	v_fmac_f32_e32 v26, v232, v205
	v_fmac_f32_e32 v25, v177, v206
	v_fmac_f32_e32 v26, v233, v206
	v_fmac_f32_e32 v25, v178, v207
	v_fmac_f32_e32 v26, v234, v207
	v_fmac_f32_e32 v25, v179, v208
	v_fmac_f32_e32 v26, v235, v208
	v_fmac_f32_e32 v25, v180, v209
	v_fmac_f32_e32 v26, v236, v209
	v_fmac_f32_e32 v25, v181, v210
	v_fmac_f32_e32 v26, v237, v210
	v_fmac_f32_e32 v25, v182, v211
	v_fmac_f32_e32 v26, v238, v211
	v_fmac_f32_e32 v25, v183, v212
	v_fmac_f32_e32 v26, v239, v212
	v_fmac_f32_e32 v25, v164, v213
	v_fmac_f32_e32 v26, v240, v213
	v_fmac_f32_e32 v25, v165, v214
	v_fmac_f32_e32 v26, v241, v214
	v_fmac_f32_e32 v25, v166, v215
	v_fmac_f32_e32 v26, v242, v215
	v_fmac_f32_e32 v25, v167, v216
	v_fmac_f32_e32 v26, v243, v216
	v_add_u32_e32 v27, s100, v27
	v_add_u32_e32 v28, s100, v28
	ds_read_b128 v[172:175], v27
	ds_read_b128 v[176:179], v27 offset:16
	ds_read_b128 v[180:183], v27 offset:32
	ds_read_b128 v[164:167], v27 offset:48
	ds_read_b128 v[228:231], v28
	ds_read_b128 v[232:235], v28 offset:16
	ds_read_b128 v[236:239], v28 offset:32
	ds_read_b128 v[240:243], v28 offset:48
	v_mul_f32_e64 v17, |v25|, s61
	v_mul_f32_e64 v18, |v26|, s61
	v_exp_f32_e32 v17, v17
	v_exp_f32_e32 v18, v18
	v_min_f32_e32 v19, 0, v25
	v_min_f32_e32 v20, 0, v26
	v_add_f32_e32 v17, 1.0, v17
	v_add_f32_e32 v18, 1.0, v18
	v_cmp_gt_f32_e64 s[4:5], s24, v17
	v_cmp_gt_f32_e64 s[6:7], s24, v18
	s_nop 1
	v_cndmask_b32_e64 v21, 0, 32, s[4:5]
	v_cndmask_b32_e64 v22, 0, 32, s[6:7]
	v_ldexp_f32 v17, v17, v21
	v_ldexp_f32 v18, v18, v22
	v_log_f32_e32 v17, v17
	v_log_f32_e32 v18, v18
	v_cndmask_b32_e64 v21, 0, v192, s[4:5]
	v_cndmask_b32_e64 v22, 0, v192, s[6:7]
	v_mul_f32_e32 v23, 0x3f317217, v17
	v_mul_f32_e32 v24, 0x3f317217, v18
	v_fma_f32 v23, v17, s62, -v23
	v_fma_f32 v24, v18, s62, -v24
	v_fmac_f32_e32 v23, 0x3377d1cf, v17
	v_fmac_f32_e32 v24, 0x3377d1cf, v18
	v_fmac_f32_e32 v23, 0x3f317217, v17
	v_fmac_f32_e32 v24, 0x3f317217, v18
	v_cmp_lt_f32_e64 s[30:31], |v17|, s63
	v_cmp_lt_f32_e64 s[36:37], |v18|, s63
	s_nop 1
	v_cndmask_b32_e64 v17, v17, v23, s[30:31]
	v_cndmask_b32_e64 v18, v18, v24, s[36:37]
	v_sub_f32_e32 v17, v17, v21
	v_sub_f32_e32 v18, v18, v22
	v_sub_f32_e32 v17, v19, v17
	v_sub_f32_e32 v18, v20, v18
	v_fma_f32 v223, v17, s2, v222
	v_fma_f32 v224, v18, s2, v223
	s_waitcnt lgkmcnt(0)
; __device__ __forceinline__ void gla_b(const Args& a, int l, int hd, int dir, int t0, unsigned char* sm, const bf16_t* __restrict__ PLR) {
;     ...
;     for (int k = 0; k < 16; ++k) {
;         const int s = q * 16 + k, j = dir ? 63 - s : s;
;         float x = Bs[d];
; #pragma unroll
;         for (int r = 0; r < 16; ++r) x += lrs[j * 16 + r] * W2s[r * 128 + d];
;         const float g = (fminf(x, 0.f) - __logf(1.f + __expf(-fabsf(x)))) * (1.f / 16.f);
;         run += g; Gb[j * 129 + d] = run;
;     }
	v_mov_b32_e32 v25, v14
	v_mov_b32_e32 v26, v14
	v_fmac_f32_e32 v25, v172, v201
	v_fmac_f32_e32 v26, v228, v201
	v_fmac_f32_e32 v25, v173, v202
	v_fmac_f32_e32 v26, v229, v202
	v_fmac_f32_e32 v25, v174, v203
	v_fmac_f32_e32 v26, v230, v203
	v_fmac_f32_e32 v25, v175, v204
	v_fmac_f32_e32 v26, v231, v204
	v_fmac_f32_e32 v25, v176, v205
	v_fmac_f32_e32 v26, v232, v205
	v_fmac_f32_e32 v25, v177, v206
	v_fmac_f32_e32 v26, v233, v206
	v_fmac_f32_e32 v25, v178, v207
	v_fmac_f32_e32 v26, v234, v207
	v_fmac_f32_e32 v25, v179, v208
	v_fmac_f32_e32 v26, v235, v208
	v_fmac_f32_e32 v25, v180, v209
	v_fmac_f32_e32 v26, v236, v209
	v_fmac_f32_e32 v25, v181, v210
	v_fmac_f32_e32 v26, v237, v210
	v_fmac_f32_e32 v25, v182, v211
	v_fmac_f32_e32 v26, v238, v211
	v_fmac_f32_e32 v25, v183, v212
	v_fmac_f32_e32 v26, v239, v212
	v_fmac_f32_e32 v25, v164, v213
	v_fmac_f32_e32 v26, v240, v213
	v_fmac_f32_e32 v25, v165, v214
	v_fmac_f32_e32 v26, v241, v214
	v_fmac_f32_e32 v25, v166, v215
	v_fmac_f32_e32 v26, v242, v215
	v_fmac_f32_e32 v25, v167, v216
	v_fmac_f32_e32 v26, v243, v216
	v_add_u32_e32 v27, s100, v27
	v_add_u32_e32 v28, s100, v28
	ds_read_b128 v[172:175], v27
	ds_read_b128 v[176:179], v27 offset:16
	ds_read_b128 v[180:183], v27 offset:32
	ds_read_b128 v[164:167], v27 offset:48
	ds_read_b128 v[228:231], v28
	ds_read_b128 v[232:235], v28 offset:16
	ds_read_b128 v[236:239], v28 offset:32
	ds_read_b128 v[240:243], v28 offset:48
	v_mul_f32_e64 v17, |v25|, s61
	v_mul_f32_e64 v18, |v26|, s61
	v_exp_f32_e32 v17, v17
	v_exp_f32_e32 v18, v18
	v_min_f32_e32 v19, 0, v25
	v_min_f32_e32 v20, 0, v26
	v_add_f32_e32 v17, 1.0, v17
	v_add_f32_e32 v18, 1.0, v18
	v_cmp_gt_f32_e64 s[4:5], s24, v17
	v_cmp_gt_f32_e64 s[6:7], s24, v18
	s_nop 1
	v_cndmask_b32_e64 v21, 0, 32, s[4:5]
	v_cndmask_b32_e64 v22, 0, 32, s[6:7]
	v_ldexp_f32 v17, v17, v21
	v_ldexp_f32 v18, v18, v22
	v_log_f32_e32 v17, v17
	v_log_f32_e32 v18, v18
	v_cndmask_b32_e64 v21, 0, v192, s[4:5]
	v_cndmask_b32_e64 v22, 0, v192, s[6:7]
	v_mul_f32_e32 v23, 0x3f317217, v17
	v_mul_f32_e32 v24, 0x3f317217, v18
	v_fma_f32 v23, v17, s62, -v23
	v_fma_f32 v24, v18, s62, -v24
	v_fmac_f32_e32 v23, 0x3377d1cf, v17
	v_fmac_f32_e32 v24, 0x3377d1cf, v18
	v_fmac_f32_e32 v23, 0x3f317217, v17
	v_fmac_f32_e32 v24, 0x3f317217, v18
	v_cmp_lt_f32_e64 s[30:31], |v17|, s63
	v_cmp_lt_f32_e64 s[36:37], |v18|, s63
	s_nop 1
	v_cndmask_b32_e64 v17, v17, v23, s[30:31]
	v_cndmask_b32_e64 v18, v18, v24, s[36:37]
	v_sub_f32_e32 v17, v17, v21
	v_sub_f32_e32 v18, v18, v22
	v_sub_f32_e32 v17, v19, v17
	v_sub_f32_e32 v18, v20, v18
	v_fma_f32 v225, v17, s2, v224
	v_fma_f32 v226, v18, s2, v225
	s_waitcnt lgkmcnt(0)
	v_mov_b32_e32 v25, v14
	v_mov_b32_e32 v26, v14
	v_fmac_f32_e32 v25, v172, v201
	v_fmac_f32_e32 v26, v228, v201
	v_fmac_f32_e32 v25, v173, v202
	v_fmac_f32_e32 v26, v229, v202
	v_fmac_f32_e32 v25, v174, v203
	v_fmac_f32_e32 v26, v230, v203
	v_fmac_f32_e32 v25, v175, v204
	v_fmac_f32_e32 v26, v231, v204
	v_fmac_f32_e32 v25, v176, v205
	v_fmac_f32_e32 v26, v232, v205
	v_fmac_f32_e32 v25, v177, v206
	v_fmac_f32_e32 v26, v233, v206
	v_fmac_f32_e32 v25, v178, v207
	v_fmac_f32_e32 v26, v234, v207
	v_fmac_f32_e32 v25, v179, v208
	v_fmac_f32_e32 v26, v235, v208
	v_fmac_f32_e32 v25, v180, v209
	v_fmac_f32_e32 v26, v236, v209
	v_fmac_f32_e32 v25, v181, v210
	v_fmac_f32_e32 v26, v237, v210
	v_fmac_f32_e32 v25, v182, v211
	v_fmac_f32_e32 v26, v238, v211
	v_fmac_f32_e32 v25, v183, v212
	v_fmac_f32_e32 v26, v239, v212
	v_fmac_f32_e32 v25, v164, v213
	v_fmac_f32_e32 v26, v240, v213
	v_fmac_f32_e32 v25, v165, v214
	v_fmac_f32_e32 v26, v241, v214
	v_fmac_f32_e32 v25, v166, v215
	v_fmac_f32_e32 v26, v242, v215
	v_fmac_f32_e32 v25, v167, v216
	v_fmac_f32_e32 v26, v243, v216
	v_add_u32_e32 v27, s100, v27
	v_add_u32_e32 v28, s100, v28
	ds_read_b128 v[172:175], v27
	ds_read_b128 v[176:179], v27 offset:16
	ds_read_b128 v[180:183], v27 offset:32
	ds_read_b128 v[164:167], v27 offset:48
	ds_read_b128 v[228:231], v28
	ds_read_b128 v[232:235], v28 offset:16
	ds_read_b128 v[236:239], v28 offset:32
	ds_read_b128 v[240:243], v28 offset:48
	v_mul_f32_e64 v17, |v25|, s61
	v_mul_f32_e64 v18, |v26|, s61
	v_exp_f32_e32 v17, v17
	v_exp_f32_e32 v18, v18
	v_min_f32_e32 v19, 0, v25
	v_min_f32_e32 v20, 0, v26
	v_add_f32_e32 v17, 1.0, v17
	v_add_f32_e32 v18, 1.0, v18
	v_cmp_gt_f32_e64 s[4:5], s24, v17
	v_cmp_gt_f32_e64 s[6:7], s24, v18
	s_nop 1
	v_cndmask_b32_e64 v21, 0, 32, s[4:5]
	v_cndmask_b32_e64 v22, 0, 32, s[6:7]
	v_ldexp_f32 v17, v17, v21
	v_ldexp_f32 v18, v18, v22
	v_log_f32_e32 v17, v17
	v_log_f32_e32 v18, v18
	v_cndmask_b32_e64 v21, 0, v192, s[4:5]
	v_cndmask_b32_e64 v22, 0, v192, s[6:7]
	v_mul_f32_e32 v23, 0x3f317217, v17
	v_mul_f32_e32 v24, 0x3f317217, v18
	v_fma_f32 v23, v17, s62, -v23
	v_fma_f32 v24, v18, s62, -v24
	v_fmac_f32_e32 v23, 0x3377d1cf, v17
	v_fmac_f32_e32 v24, 0x3377d1cf, v18
	v_fmac_f32_e32 v23, 0x3f317217, v17
	v_fmac_f32_e32 v24, 0x3f317217, v18
	v_cmp_lt_f32_e64 s[30:31], |v17|, s63
	v_cmp_lt_f32_e64 s[36:37], |v18|, s63
	s_nop 1
	v_cndmask_b32_e64 v17, v17, v23, s[30:31]
	v_cndmask_b32_e64 v18, v18, v24, s[36:37]
	v_sub_f32_e32 v17, v17, v21
	v_sub_f32_e32 v18, v18, v22
	v_sub_f32_e32 v17, v19, v17
	v_sub_f32_e32 v18, v20, v18
	v_fma_f32 v227, v17, s2, v226
	v_fma_f32 v184, v18, s2, v227
	s_waitcnt lgkmcnt(0)
; __device__ __forceinline__ void gla_b(const Args& a, int l, int hd, int dir, int t0, unsigned char* sm, const bf16_t* __restrict__ PLR) {
;     ...
;     for (int k = 0; k < 16; ++k) {
;         const int s = q * 16 + k, j = dir ? 63 - s : s;
;         float x = Bs[d];
; #pragma unroll
;         for (int r = 0; r < 16; ++r) x += lrs[j * 16 + r] * W2s[r * 128 + d];
;         const float g = (fminf(x, 0.f) - __logf(1.f + __expf(-fabsf(x)))) * (1.f / 16.f);
;         run += g; Gb[j * 129 + d] = run;
;     }
;     tot[q * 128 + d] = run;
	v_mov_b32_e32 v25, v14
	v_mov_b32_e32 v26, v14
	v_fmac_f32_e32 v25, v172, v201
	v_fmac_f32_e32 v26, v228, v201
	v_fmac_f32_e32 v25, v173, v202
	v_fmac_f32_e32 v26, v229, v202
	v_fmac_f32_e32 v25, v174, v203
	v_fmac_f32_e32 v26, v230, v203
	v_fmac_f32_e32 v25, v175, v204
	v_fmac_f32_e32 v26, v231, v204
	v_fmac_f32_e32 v25, v176, v205
	v_fmac_f32_e32 v26, v232, v205
	v_fmac_f32_e32 v25, v177, v206
	v_fmac_f32_e32 v26, v233, v206
	v_fmac_f32_e32 v25, v178, v207
	v_fmac_f32_e32 v26, v234, v207
	v_fmac_f32_e32 v25, v179, v208
	v_fmac_f32_e32 v26, v235, v208
	v_fmac_f32_e32 v25, v180, v209
	v_fmac_f32_e32 v26, v236, v209
	v_fmac_f32_e32 v25, v181, v210
	v_fmac_f32_e32 v26, v237, v210
	v_fmac_f32_e32 v25, v182, v211
	v_fmac_f32_e32 v26, v238, v211
	v_fmac_f32_e32 v25, v183, v212
	v_fmac_f32_e32 v26, v239, v212
	v_fmac_f32_e32 v25, v164, v213
	v_fmac_f32_e32 v26, v240, v213
	v_fmac_f32_e32 v25, v165, v214
	v_fmac_f32_e32 v26, v241, v214
	v_fmac_f32_e32 v25, v166, v215
	v_fmac_f32_e32 v26, v242, v215
	v_fmac_f32_e32 v25, v167, v216
	v_fmac_f32_e32 v26, v243, v216
	v_add_u32_e32 v27, s100, v27
	v_add_u32_e32 v28, s100, v28
	ds_read_b128 v[172:175], v27
	ds_read_b128 v[176:179], v27 offset:16
	ds_read_b128 v[180:183], v27 offset:32
	ds_read_b128 v[164:167], v27 offset:48
	ds_read_b128 v[228:231], v28
	ds_read_b128 v[232:235], v28 offset:16
	ds_read_b128 v[236:239], v28 offset:32
	ds_read_b128 v[240:243], v28 offset:48
	v_mul_f32_e64 v17, |v25|, s61
	v_mul_f32_e64 v18, |v26|, s61
	v_exp_f32_e32 v17, v17
	v_exp_f32_e32 v18, v18
	v_min_f32_e32 v19, 0, v25
	v_min_f32_e32 v20, 0, v26
	v_add_f32_e32 v17, 1.0, v17
	v_add_f32_e32 v18, 1.0, v18
	v_cmp_gt_f32_e64 s[4:5], s24, v17
	v_cmp_gt_f32_e64 s[6:7], s24, v18
	s_nop 1
	v_cndmask_b32_e64 v21, 0, 32, s[4:5]
	v_cndmask_b32_e64 v22, 0, 32, s[6:7]
	v_ldexp_f32 v17, v17, v21
	v_ldexp_f32 v18, v18, v22
	v_log_f32_e32 v17, v17
	v_log_f32_e32 v18, v18
	v_cndmask_b32_e64 v21, 0, v192, s[4:5]
	v_cndmask_b32_e64 v22, 0, v192, s[6:7]
	v_mul_f32_e32 v23, 0x3f317217, v17
	v_mul_f32_e32 v24, 0x3f317217, v18
	v_fma_f32 v23, v17, s62, -v23
	v_fma_f32 v24, v18, s62, -v24
	v_fmac_f32_e32 v23, 0x3377d1cf, v17
	v_fmac_f32_e32 v24, 0x3377d1cf, v18
	v_fmac_f32_e32 v23, 0x3f317217, v17
	v_fmac_f32_e32 v24, 0x3f317217, v18
	v_cmp_lt_f32_e64 s[30:31], |v17|, s63
	v_cmp_lt_f32_e64 s[36:37], |v18|, s63
	s_nop 1
	v_cndmask_b32_e64 v17, v17, v23, s[30:31]
	v_cndmask_b32_e64 v18, v18, v24, s[36:37]
	v_sub_f32_e32 v17, v17, v21
	v_sub_f32_e32 v18, v18, v22
	v_sub_f32_e32 v17, v19, v17
	v_sub_f32_e32 v18, v20, v18
	v_fma_f32 v185, v17, s2, v184
	v_fma_f32 v162, v18, s2, v185
	s_waitcnt lgkmcnt(0)
	v_mov_b32_e32 v25, v14
	v_mov_b32_e32 v26, v14
	v_fmac_f32_e32 v25, v172, v201
	v_fmac_f32_e32 v26, v228, v201
	v_fmac_f32_e32 v25, v173, v202
	v_fmac_f32_e32 v26, v229, v202
	v_fmac_f32_e32 v25, v174, v203
	v_fmac_f32_e32 v26, v230, v203
	v_fmac_f32_e32 v25, v175, v204
	v_fmac_f32_e32 v26, v231, v204
	v_fmac_f32_e32 v25, v176, v205
	v_fmac_f32_e32 v26, v232, v205
	v_fmac_f32_e32 v25, v177, v206
	v_fmac_f32_e32 v26, v233, v206
	v_fmac_f32_e32 v25, v178, v207
	v_fmac_f32_e32 v26, v234, v207
	v_fmac_f32_e32 v25, v179, v208
	v_fmac_f32_e32 v26, v235, v208
	v_fmac_f32_e32 v25, v180, v209
	v_fmac_f32_e32 v26, v236, v209
	v_fmac_f32_e32 v25, v181, v210
	v_fmac_f32_e32 v26, v237, v210
	v_fmac_f32_e32 v25, v182, v211
	v_fmac_f32_e32 v26, v238, v211
	v_fmac_f32_e32 v25, v183, v212
	v_fmac_f32_e32 v26, v239, v212
	v_fmac_f32_e32 v25, v164, v213
	v_fmac_f32_e32 v26, v240, v213
	v_fmac_f32_e32 v25, v165, v214
	v_fmac_f32_e32 v26, v241, v214
	v_fmac_f32_e32 v25, v166, v215
	v_fmac_f32_e32 v26, v242, v215
	v_fmac_f32_e32 v25, v167, v216
	v_fmac_f32_e32 v26, v243, v216
	v_mul_f32_e64 v17, |v25|, s61
	v_mul_f32_e64 v18, |v26|, s61
	v_exp_f32_e32 v17, v17
	v_exp_f32_e32 v18, v18
	v_min_f32_e32 v19, 0, v25
	v_min_f32_e32 v20, 0, v26
	v_add_f32_e32 v17, 1.0, v17
	v_add_f32_e32 v18, 1.0, v18
	v_cmp_gt_f32_e64 s[4:5], s24, v17
	v_cmp_gt_f32_e64 s[6:7], s24, v18
	s_nop 1
	v_cndmask_b32_e64 v21, 0, 32, s[4:5]
	v_cndmask_b32_e64 v22, 0, 32, s[6:7]
	v_ldexp_f32 v17, v17, v21
	v_ldexp_f32 v18, v18, v22
	v_log_f32_e32 v17, v17
	v_log_f32_e32 v18, v18
	v_cndmask_b32_e64 v21, 0, v192, s[4:5]
	v_cndmask_b32_e64 v22, 0, v192, s[6:7]
	v_mul_f32_e32 v23, 0x3f317217, v17
	v_mul_f32_e32 v24, 0x3f317217, v18
	v_fma_f32 v23, v17, s62, -v23
	v_fma_f32 v24, v18, s62, -v24
	v_fmac_f32_e32 v23, 0x3377d1cf, v17
	v_fmac_f32_e32 v24, 0x3377d1cf, v18
	v_fmac_f32_e32 v23, 0x3f317217, v17
	v_fmac_f32_e32 v24, 0x3f317217, v18
	v_cmp_lt_f32_e64 s[30:31], |v17|, s63
	v_cmp_lt_f32_e64 s[36:37], |v18|, s63
	s_nop 1
	v_cndmask_b32_e64 v17, v17, v23, s[30:31]
	v_cndmask_b32_e64 v18, v18, v24, s[36:37]
	v_sub_f32_e32 v17, v17, v21
	v_sub_f32_e32 v18, v18, v22
	v_sub_f32_e32 v17, v19, v17
	v_sub_f32_e32 v18, v20, v18
	v_fma_f32 v163, v17, s2, v162
	v_fma_f32 v168, v18, s2, v163
	ds_write_b32 v9, v168 offset:45824
	s_waitcnt lgkmcnt(0)
	s_barrier
; __device__ __forceinline__ void gla_b(const Args& a, int l, int hd, int dir, int t0, unsigned char* sm, const bf16_t* __restrict__ PLR) {
;     ...
;     tot[q * 128 + d] = run;
;     __syncthreads();
;     float off = 0.f;
;     for (int qq = 0; qq < q; ++qq) off += tot[qq * 128 + d];
;     if (q > 0) for (int k = 0; k < 16; ++k) { const int s = q * 16 + k, j = dir ? 63 - s : s; Gb[j * 129 + d] += off; }
;     __syncthreads();
	ds_read_b32 v17, v8 offset:45824
	ds_read_b32 v18, v8 offset:46336
	ds_read_b32 v19, v8 offset:46848
	v_lshrrev_b32_e32 v15, 7, v171
	v_cmp_lt_u32_e64 s[4:5], 0, v15
	v_cmp_lt_u32_e64 s[6:7], 1, v15
	v_cmp_lt_u32_e64 s[30:31], 2, v15
	s_waitcnt lgkmcnt(0)
	v_cndmask_b32_e64 v17, 0, v17, s[4:5]
	v_cndmask_b32_e64 v18, 0, v18, s[6:7]
	v_cndmask_b32_e64 v19, 0, v19, s[30:31]
	v_add_f32_e32 v17, v17, v18
	v_add_f32_e32 v17, v17, v19
	v_add_f32_e32 v21, v217, v17
	ds_write_b32 v16, v21
	v_add_u32_e32 v16, s101, v16
	v_add_f32_e32 v22, v218, v17
	ds_write_b32 v16, v22
	v_add_u32_e32 v16, s101, v16
	v_add_f32_e32 v21, v219, v17
	ds_write_b32 v16, v21
	v_add_u32_e32 v16, s101, v16
	v_add_f32_e32 v22, v220, v17
	ds_write_b32 v16, v22
	v_add_u32_e32 v16, s101, v16
	v_add_f32_e32 v21, v221, v17
	ds_write_b32 v16, v21
	v_add_u32_e32 v16, s101, v16
	v_add_f32_e32 v22, v222, v17
	ds_write_b32 v16, v22
	v_add_u32_e32 v16, s101, v16
	v_add_f32_e32 v21, v223, v17
	ds_write_b32 v16, v21
	v_add_u32_e32 v16, s101, v16
	v_add_f32_e32 v22, v224, v17
	ds_write_b32 v16, v22
	v_add_u32_e32 v16, s101, v16
	v_add_f32_e32 v21, v225, v17
	ds_write_b32 v16, v21
	v_add_u32_e32 v16, s101, v16
	v_add_f32_e32 v22, v226, v17
	ds_write_b32 v16, v22
	v_add_u32_e32 v16, s101, v16
	v_add_f32_e32 v21, v227, v17
	ds_write_b32 v16, v21
	v_add_u32_e32 v16, s101, v16
	v_add_f32_e32 v22, v184, v17
	ds_write_b32 v16, v22
	v_add_u32_e32 v16, s101, v16
	v_add_f32_e32 v21, v185, v17
	ds_write_b32 v16, v21
	v_add_u32_e32 v16, s101, v16
	v_add_f32_e32 v22, v162, v17
	ds_write_b32 v16, v22
	v_add_u32_e32 v16, s101, v16
	v_add_f32_e32 v21, v163, v17
	ds_write_b32 v16, v21
	v_add_u32_e32 v16, s101, v16
	v_add_f32_e32 v22, v168, v17
	ds_write_b32 v16, v22
	s_cmpk_lt_u32 s28, 0x400
	s_cselect_b64 s[0:1], -1, 0
	s_mov_b64 s[6:7], exec
	v_readlane_b32 s64, v248, 45
	v_readlane_b32 s65, v248, 46
	v_readlane_b32 s66, v248, 47
	v_readlane_b32 s67, v248, 48
	v_readlane_b32 s68, v248, 49
	v_readlane_b32 s69, v248, 50
	v_readlane_b32 s70, v248, 51
	v_readlane_b32 s71, v248, 52
	v_readlane_b32 s72, v248, 53
	v_readlane_b32 s73, v248, 54
	v_readlane_b32 s74, v248, 55
	v_readlane_b32 s75, v248, 56
	v_readlane_b32 s76, v248, 57
	v_readlane_b32 s77, v248, 58
	v_readlane_b32 s78, v248, 59
	v_readlane_b32 s79, v248, 60

; __device__ __forceinline__ int ltid() { int t = threadIdx.x; asm volatile("" : "+v"(t)); return t; }
; __device__ __forceinline__ void gla_scan(bf16_t* __restrict__ UPD, const float* __restrict__ DEC) {
;     for (int idx = blockIdx.x * 512 + ltid(); idx < 131072; idx += gridDim.x * 512) {
;         const int combo = idx >> 14, rem = idx & 16383, dv = rem >> 6, dk = (rem & 63) * 2, dir = combo >> 2;
;         unsigned* up = (unsigned*)(UPD + (size_t)combo * 256 * 32768 + dv * 128 + dk);
;         const float* dp = DEC + (size_t)combo * 256 * 128 + dk;
;         float s0 = 0.f, s1 = 0.f;
;         unsigned uv[8], un[8]; float2 dc[8], dn[8];
; #pragma unroll
;         for (int k = 0; k < 8; ++k) { const int n = dir ? 255 - k : k; uv[k] = up[(size_t)n * 16384]; dc[k] = *(const float2*)(dp + n * 128); }
.LBB0_288:
	v_readfirstlane_b32 s100, v38
	v_readlane_b32 s26, v246, 31
	v_readlane_b32 s27, v246, 32
	v_readlane_b32 s28, v246, 33
	v_readlane_b32 s29, v246, 34
	s_nop 3
	s_lshr_b32 s101, s100, 14
	s_lshl_b32 s20, s101, 24
	s_add_u32 s26, s26, s20
	s_addc_u32 s27, s27, 0
	s_lshl_b32 s20, s101, 17
	s_add_u32 s28, s28, s20
	s_addc_u32 s29, s29, 0
	s_bitcmp1_b32 s101, 2
	s_cbranch_scc0 .Lscan_fwd
	s_add_u32 s26, s26, 0xff0000
	s_addc_u32 s27, s27, 0
	s_add_u32 s28, s28, 0x1fe00
	s_addc_u32 s29, s29, 0
	s_mov_b32 s2, 0xffff0000
	s_mov_b32 s3, -1
	s_mov_b32 s20, 0xfffffe00
	s_branch .Lscan_go
.Lscan_fwd:
	s_mov_b32 s2, 0x10000
	s_mov_b32 s3, 0
	s_movk_i32 s20, 0x200
.Lscan_go:
	s_mov_b64 s[0:1], s[26:27]
	v_and_b32_e32 v0, 0x3fff, v38
	v_lshlrev_b32_e32 v0, 2, v0
	v_and_b32_e32 v1, 63, v38
	v_lshlrev_b32_e32 v1, 3, v1
	v_mov_b32_e32 v2, 0
	v_mov_b32_e32 v3, 0
	global_load_dword v8, v0, s[26:27]
	global_load_dwordx2 v[66:67], v1, s[28:29]
	s_add_u32 s26, s26, s2
	s_addc_u32 s27, s27, s3
	s_add_u32 s28, s28, s20
	s_addc_u32 s29, s29, s3
	global_load_dword v9, v0, s[26:27]
	global_load_dwordx2 v[68:69], v1, s[28:29]
	s_add_u32 s26, s26, s2
	s_addc_u32 s27, s27, s3
	s_add_u32 s28, s28, s20
	s_addc_u32 s29, s29, s3
	global_load_dword v10, v0, s[26:27]
	global_load_dwordx2 v[70:71], v1, s[28:29]
	s_add_u32 s26, s26, s2
	s_addc_u32 s27, s27, s3
	s_add_u32 s28, s28, s20
	s_addc_u32 s29, s29, s3
	global_load_dword v11, v0, s[26:27]
	global_load_dwordx2 v[72:73], v1, s[28:29]
	s_add_u32 s26, s26, s2
	s_addc_u32 s27, s27, s3
	s_add_u32 s28, s28, s20
	s_addc_u32 s29, s29, s3
	global_load_dword v12, v0, s[26:27]
	global_load_dwordx2 v[74:75], v1, s[28:29]
	s_add_u32 s26, s26, s2
	s_addc_u32 s27, s27, s3
	s_add_u32 s28, s28, s20
	s_addc_u32 s29, s29, s3
	global_load_dword v13, v0, s[26:27]
	global_load_dwordx2 v[76:77], v1, s[28:29]
	s_add_u32 s26, s26, s2
	s_addc_u32 s27, s27, s3
	s_add_u32 s28, s28, s20
	s_addc_u32 s29, s29, s3
	global_load_dword v14, v0, s[26:27]
	global_load_dwordx2 v[78:79], v1, s[28:29]
	s_add_u32 s26, s26, s2
	s_addc_u32 s27, s27, s3
	s_add_u32 s28, s28, s20
	s_addc_u32 s29, s29, s3
	global_load_dword v15, v0, s[26:27]
	global_load_dwordx2 v[80:81], v1, s[28:29]
	s_add_u32 s26, s26, s2
	s_addc_u32 s27, s27, s3
	s_add_u32 s28, s28, s20
	s_addc_u32 s29, s29, s3
	global_load_dword v16, v0, s[26:27]
	global_load_dwordx2 v[82:83], v1, s[28:29]
	s_add_u32 s26, s26, s2
	s_addc_u32 s27, s27, s3
	s_add_u32 s28, s28, s20
	s_addc_u32 s29, s29, s3
	global_load_dword v17, v0, s[26:27]
	global_load_dwordx2 v[84:85], v1, s[28:29]
	s_add_u32 s26, s26, s2
	s_addc_u32 s27, s27, s3
	s_add_u32 s28, s28, s20
	s_addc_u32 s29, s29, s3
	global_load_dword v18, v0, s[26:27]
	global_load_dwordx2 v[86:87], v1, s[28:29]
	s_add_u32 s26, s26, s2
	s_addc_u32 s27, s27, s3
	s_add_u32 s28, s28, s20
	s_addc_u32 s29, s29, s3
	global_load_dword v19, v0, s[26:27]
	global_load_dwordx2 v[88:89], v1, s[28:29]
	s_add_u32 s26, s26, s2
	s_addc_u32 s27, s27, s3
	s_add_u32 s28, s28, s20
	s_addc_u32 s29, s29, s3
	global_load_dword v20, v0, s[26:27]
	global_load_dwordx2 v[90:91], v1, s[28:29]
	s_add_u32 s26, s26, s2
	s_addc_u32 s27, s27, s3
	s_add_u32 s28, s28, s20
	s_addc_u32 s29, s29, s3
	global_load_dword v21, v0, s[26:27]
	global_load_dwordx2 v[92:93], v1, s[28:29]
	s_add_u32 s26, s26, s2
	s_addc_u32 s27, s27, s3
	s_add_u32 s28, s28, s20
	s_addc_u32 s29, s29, s3
	global_load_dword v22, v0, s[26:27]
	global_load_dwordx2 v[94:95], v1, s[28:29]
	s_add_u32 s26, s26, s2
	s_addc_u32 s27, s27, s3
	s_add_u32 s28, s28, s20
	s_addc_u32 s29, s29, s3
	global_load_dword v23, v0, s[26:27]
	global_load_dwordx2 v[96:97], v1, s[28:29]
	s_add_u32 s26, s26, s2
	s_addc_u32 s27, s27, s3
	s_add_u32 s28, s28, s20
	s_addc_u32 s29, s29, s3
	global_load_dword v40, v0, s[26:27]
	global_load_dwordx2 v[98:99], v1, s[28:29]
	s_add_u32 s26, s26, s2
	s_addc_u32 s27, s27, s3
	s_add_u32 s28, s28, s20
	s_addc_u32 s29, s29, s3
	global_load_dword v41, v0, s[26:27]
	global_load_dwordx2 v[100:101], v1, s[28:29]
	s_add_u32 s26, s26, s2
	s_addc_u32 s27, s27, s3
	s_add_u32 s28, s28, s20
	s_addc_u32 s29, s29, s3
	global_load_dword v42, v0, s[26:27]
	global_load_dwordx2 v[102:103], v1, s[28:29]
	s_add_u32 s26, s26, s2
	s_addc_u32 s27, s27, s3
	s_add_u32 s28, s28, s20
	s_addc_u32 s29, s29, s3
	global_load_dword v43, v0, s[26:27]
	global_load_dwordx2 v[104:105], v1, s[28:29]
	s_add_u32 s26, s26, s2
	s_addc_u32 s27, s27, s3
	s_add_u32 s28, s28, s20
	s_addc_u32 s29, s29, s3
	global_load_dword v44, v0, s[26:27]
	global_load_dwordx2 v[106:107], v1, s[28:29]
	s_add_u32 s26, s26, s2
	s_addc_u32 s27, s27, s3
	s_add_u32 s28, s28, s20
	s_addc_u32 s29, s29, s3
	global_load_dword v45, v0, s[26:27]
	global_load_dwordx2 v[108:109], v1, s[28:29]
	s_add_u32 s26, s26, s2
	s_addc_u32 s27, s27, s3
	s_add_u32 s28, s28, s20
	s_addc_u32 s29, s29, s3
	global_load_dword v46, v0, s[26:27]
	global_load_dwordx2 v[110:111], v1, s[28:29]
	s_add_u32 s26, s26, s2
	s_addc_u32 s27, s27, s3
	s_add_u32 s28, s28, s20
	s_addc_u32 s29, s29, s3
	global_load_dword v47, v0, s[26:27]
	global_load_dwordx2 v[112:113], v1, s[28:29]
	s_add_u32 s26, s26, s2
	s_addc_u32 s27, s27, s3
	s_add_u32 s28, s28, s20
	s_addc_u32 s29, s29, s3
	global_load_dword v48, v0, s[26:27]
	global_load_dwordx2 v[114:115], v1, s[28:29]
	s_add_u32 s26, s26, s2
	s_addc_u32 s27, s27, s3
	s_add_u32 s28, s28, s20
	s_addc_u32 s29, s29, s3
	global_load_dword v49, v0, s[26:27]
	global_load_dwordx2 v[116:117], v1, s[28:29]
	s_add_u32 s26, s26, s2
	s_addc_u32 s27, s27, s3
	s_add_u32 s28, s28, s20
	s_addc_u32 s29, s29, s3
	global_load_dword v50, v0, s[26:27]
	global_load_dwordx2 v[118:119], v1, s[28:29]
	s_add_u32 s26, s26, s2
	s_addc_u32 s27, s27, s3
	s_add_u32 s28, s28, s20
	s_addc_u32 s29, s29, s3
	global_load_dword v51, v0, s[26:27]
	global_load_dwordx2 v[120:121], v1, s[28:29]
	s_add_u32 s26, s26, s2
	s_addc_u32 s27, s27, s3
	s_add_u32 s28, s28, s20
	s_addc_u32 s29, s29, s3
	global_load_dword v52, v0, s[26:27]
	global_load_dwordx2 v[122:123], v1, s[28:29]
	s_add_u32 s26, s26, s2
	s_addc_u32 s27, s27, s3
	s_add_u32 s28, s28, s20
	s_addc_u32 s29, s29, s3
	global_load_dword v53, v0, s[26:27]
	global_load_dwordx2 v[124:125], v1, s[28:29]
	s_add_u32 s26, s26, s2
	s_addc_u32 s27, s27, s3
	s_add_u32 s28, s28, s20
	s_addc_u32 s29, s29, s3
	global_load_dword v54, v0, s[26:27]
	global_load_dwordx2 v[126:127], v1, s[28:29]
	s_add_u32 s26, s26, s2
	s_addc_u32 s27, s27, s3
	s_add_u32 s28, s28, s20
	s_addc_u32 s29, s29, s3
	global_load_dword v55, v0, s[26:27]
	global_load_dwordx2 v[128:129], v1, s[28:29]
	s_add_u32 s26, s26, s2
	s_addc_u32 s27, s27, s3
	s_add_u32 s28, s28, s20
	s_addc_u32 s29, s29, s3
	s_waitcnt vmcnt(32)
	s_mov_b32 s100, 0
; __device__ __forceinline__ unsigned pk2(float lo, float hi) { unsigned r; asm volatile("v_cvt_pk_bf16_f32 %0, %1, %2" : "=v"(r) : "v"(lo), "v"(hi)); return r; }
; __device__ __forceinline__ float bflo(unsigned w) { return __uint_as_float(w << 16); }
; __device__ __forceinline__ float bfhi(unsigned w) { return __uint_as_float(w & 0xffff0000u); }
; __device__ __forceinline__ void gla_scan(bf16_t* __restrict__ UPD, const float* __restrict__ DEC) {
;     ...
;         for (int nb = 0; nb < 256; nb += 8) {
;             if (nb + 8 < 256) {
; #pragma unroll
;                 for (int k = 0; k < 8; ++k) { const int n = dir ? 255 - (nb + 8 + k) : nb + 8 + k; un[k] = up[(size_t)n * 16384]; dn[k] = *(const float2*)(dp + n * 128); }
;             }
; #pragma unroll
;             for (int k = 0; k < 8; ++k) { const int n = dir ? 255 - (nb + k) : nb + k; up[(size_t)n * 16384] = pk2(s0, s1); s0 = dc[k].x * s0 + bflo(uv[k]); s1 = dc[k].y * s1 + bfhi(uv[k]); }
; #pragma unroll
;             for (int k = 0; k < 8; ++k) { uv[k] = un[k]; dc[k] = dn[k]; }
;         }
.Lscan_loop:
	s_waitcnt vmcnt(48)
	v_cvt_pk_bf16_f32 v4, v2, v3
	global_store_dword v0, v4, s[0:1]
	s_add_u32 s0, s0, s2
	s_addc_u32 s1, s1, s3
	v_lshlrev_b32_e32 v5, 16, v8
	v_and_b32_e32 v6, 0xffff0000, v8
	v_fma_f32 v2, v66, v2, v5
	v_fma_f32 v3, v67, v3, v6
	v_cvt_pk_bf16_f32 v56, v2, v3
	global_store_dword v0, v56, s[0:1]
	s_add_u32 s0, s0, s2
	s_addc_u32 s1, s1, s3
	v_lshlrev_b32_e32 v57, 16, v9
	v_and_b32_e32 v58, 0xffff0000, v9
	v_fma_f32 v2, v68, v2, v57
	v_fma_f32 v3, v69, v3, v58
	v_cvt_pk_bf16_f32 v4, v2, v3
	global_store_dword v0, v4, s[0:1]
	s_add_u32 s0, s0, s2
	s_addc_u32 s1, s1, s3
	v_lshlrev_b32_e32 v5, 16, v10
	v_and_b32_e32 v6, 0xffff0000, v10
	v_fma_f32 v2, v70, v2, v5
	v_fma_f32 v3, v71, v3, v6
	v_cvt_pk_bf16_f32 v56, v2, v3
	global_store_dword v0, v56, s[0:1]
	s_add_u32 s0, s0, s2
	s_addc_u32 s1, s1, s3
	v_lshlrev_b32_e32 v57, 16, v11
	v_and_b32_e32 v58, 0xffff0000, v11
	v_fma_f32 v2, v72, v2, v57
	v_fma_f32 v3, v73, v3, v58
	v_cvt_pk_bf16_f32 v4, v2, v3
	global_store_dword v0, v4, s[0:1]
	s_add_u32 s0, s0, s2
	s_addc_u32 s1, s1, s3
	v_lshlrev_b32_e32 v5, 16, v12
	v_and_b32_e32 v6, 0xffff0000, v12
	v_fma_f32 v2, v74, v2, v5
	v_fma_f32 v3, v75, v3, v6
	v_cvt_pk_bf16_f32 v56, v2, v3
	global_store_dword v0, v56, s[0:1]
	s_add_u32 s0, s0, s2
	s_addc_u32 s1, s1, s3
	v_lshlrev_b32_e32 v57, 16, v13
	v_and_b32_e32 v58, 0xffff0000, v13
	v_fma_f32 v2, v76, v2, v57
	v_fma_f32 v3, v77, v3, v58
	v_cvt_pk_bf16_f32 v4, v2, v3
	global_store_dword v0, v4, s[0:1]
	s_add_u32 s0, s0, s2
	s_addc_u32 s1, s1, s3
	v_lshlrev_b32_e32 v5, 16, v14
	v_and_b32_e32 v6, 0xffff0000, v14
	v_fma_f32 v2, v78, v2, v5
	v_fma_f32 v3, v79, v3, v6
	v_cvt_pk_bf16_f32 v56, v2, v3
	global_store_dword v0, v56, s[0:1]
	s_add_u32 s0, s0, s2
	s_addc_u32 s1, s1, s3
	v_lshlrev_b32_e32 v57, 16, v15
	v_and_b32_e32 v58, 0xffff0000, v15
	v_fma_f32 v2, v80, v2, v57
	v_fma_f32 v3, v81, v3, v58
	v_cvt_pk_bf16_f32 v4, v2, v3
	global_store_dword v0, v4, s[0:1]
	s_add_u32 s0, s0, s2
	s_addc_u32 s1, s1, s3
	v_lshlrev_b32_e32 v5, 16, v16
	v_and_b32_e32 v6, 0xffff0000, v16
	v_fma_f32 v2, v82, v2, v5
	v_fma_f32 v3, v83, v3, v6
	v_cvt_pk_bf16_f32 v56, v2, v3
	global_store_dword v0, v56, s[0:1]
	s_add_u32 s0, s0, s2
	s_addc_u32 s1, s1, s3
	v_lshlrev_b32_e32 v57, 16, v17
	v_and_b32_e32 v58, 0xffff0000, v17
	v_fma_f32 v2, v84, v2, v57
	v_fma_f32 v3, v85, v3, v58
	v_cvt_pk_bf16_f32 v4, v2, v3
	global_store_dword v0, v4, s[0:1]
	s_add_u32 s0, s0, s2
	s_addc_u32 s1, s1, s3
	v_lshlrev_b32_e32 v5, 16, v18
	v_and_b32_e32 v6, 0xffff0000, v18
	v_fma_f32 v2, v86, v2, v5
	v_fma_f32 v3, v87, v3, v6
	v_cvt_pk_bf16_f32 v56, v2, v3
	global_store_dword v0, v56, s[0:1]
	s_add_u32 s0, s0, s2
	s_addc_u32 s1, s1, s3
	v_lshlrev_b32_e32 v57, 16, v19
	v_and_b32_e32 v58, 0xffff0000, v19
	v_fma_f32 v2, v88, v2, v57
	v_fma_f32 v3, v89, v3, v58
	v_cvt_pk_bf16_f32 v4, v2, v3
	global_store_dword v0, v4, s[0:1]
	s_add_u32 s0, s0, s2
	s_addc_u32 s1, s1, s3
	v_lshlrev_b32_e32 v5, 16, v20
	v_and_b32_e32 v6, 0xffff0000, v20
	v_fma_f32 v2, v90, v2, v5
	v_fma_f32 v3, v91, v3, v6
	v_cvt_pk_bf16_f32 v56, v2, v3
	global_store_dword v0, v56, s[0:1]
	s_add_u32 s0, s0, s2
	s_addc_u32 s1, s1, s3
	v_lshlrev_b32_e32 v57, 16, v21
	v_and_b32_e32 v58, 0xffff0000, v21
	v_fma_f32 v2, v92, v2, v57
	v_fma_f32 v3, v93, v3, v58
	v_cvt_pk_bf16_f32 v4, v2, v3
	global_store_dword v0, v4, s[0:1]
	s_add_u32 s0, s0, s2
	s_addc_u32 s1, s1, s3
	v_lshlrev_b32_e32 v5, 16, v22
	v_and_b32_e32 v6, 0xffff0000, v22
	v_fma_f32 v2, v94, v2, v5
	v_fma_f32 v3, v95, v3, v6
	v_cvt_pk_bf16_f32 v56, v2, v3
	global_store_dword v0, v56, s[0:1]
	s_add_u32 s0, s0, s2
	s_addc_u32 s1, s1, s3
	v_lshlrev_b32_e32 v57, 16, v23
	v_and_b32_e32 v58, 0xffff0000, v23
	v_fma_f32 v2, v96, v2, v57
	v_fma_f32 v3, v97, v3, v58
	s_cmp_eq_u32 s100, 7
	s_cbranch_scc1 .Lscan_skipA
	global_load_dword v8, v0, s[26:27]
	global_load_dwordx2 v[66:67], v1, s[28:29]
	s_add_u32 s26, s26, s2
	s_addc_u32 s27, s27, s3
	s_add_u32 s28, s28, s20
	s_addc_u32 s29, s29, s3
	global_load_dword v9, v0, s[26:27]
	global_load_dwordx2 v[68:69], v1, s[28:29]
	s_add_u32 s26, s26, s2
	s_addc_u32 s27, s27, s3
	s_add_u32 s28, s28, s20
	s_addc_u32 s29, s29, s3
	global_load_dword v10, v0, s[26:27]
	global_load_dwordx2 v[70:71], v1, s[28:29]
	s_add_u32 s26, s26, s2
	s_addc_u32 s27, s27, s3
	s_add_u32 s28, s28, s20
	s_addc_u32 s29, s29, s3
	global_load_dword v11, v0, s[26:27]
	global_load_dwordx2 v[72:73], v1, s[28:29]
	s_add_u32 s26, s26, s2
	s_addc_u32 s27, s27, s3
	s_add_u32 s28, s28, s20
	s_addc_u32 s29, s29, s3
	global_load_dword v12, v0, s[26:27]
	global_load_dwordx2 v[74:75], v1, s[28:29]
	s_add_u32 s26, s26, s2
	s_addc_u32 s27, s27, s3
	s_add_u32 s28, s28, s20
	s_addc_u32 s29, s29, s3
	global_load_dword v13, v0, s[26:27]
	global_load_dwordx2 v[76:77], v1, s[28:29]
	s_add_u32 s26, s26, s2
	s_addc_u32 s27, s27, s3
	s_add_u32 s28, s28, s20
	s_addc_u32 s29, s29, s3
	global_load_dword v14, v0, s[26:27]
	global_load_dwordx2 v[78:79], v1, s[28:29]
	s_add_u32 s26, s26, s2
	s_addc_u32 s27, s27, s3
	s_add_u32 s28, s28, s20
	s_addc_u32 s29, s29, s3
	global_load_dword v15, v0, s[26:27]
	global_load_dwordx2 v[80:81], v1, s[28:29]
	s_add_u32 s26, s26, s2
	s_addc_u32 s27, s27, s3
	s_add_u32 s28, s28, s20
	s_addc_u32 s29, s29, s3
	global_load_dword v16, v0, s[26:27]
	global_load_dwordx2 v[82:83], v1, s[28:29]
	s_add_u32 s26, s26, s2
	s_addc_u32 s27, s27, s3
	s_add_u32 s28, s28, s20
	s_addc_u32 s29, s29, s3
	global_load_dword v17, v0, s[26:27]
	global_load_dwordx2 v[84:85], v1, s[28:29]
	s_add_u32 s26, s26, s2
	s_addc_u32 s27, s27, s3
	s_add_u32 s28, s28, s20
	s_addc_u32 s29, s29, s3
	global_load_dword v18, v0, s[26:27]
	global_load_dwordx2 v[86:87], v1, s[28:29]
	s_add_u32 s26, s26, s2
	s_addc_u32 s27, s27, s3
	s_add_u32 s28, s28, s20
	s_addc_u32 s29, s29, s3
	global_load_dword v19, v0, s[26:27]
	global_load_dwordx2 v[88:89], v1, s[28:29]
	s_add_u32 s26, s26, s2
	s_addc_u32 s27, s27, s3
	s_add_u32 s28, s28, s20
	s_addc_u32 s29, s29, s3
	global_load_dword v20, v0, s[26:27]
	global_load_dwordx2 v[90:91], v1, s[28:29]
	s_add_u32 s26, s26, s2
	s_addc_u32 s27, s27, s3
	s_add_u32 s28, s28, s20
	s_addc_u32 s29, s29, s3
	global_load_dword v21, v0, s[26:27]
	global_load_dwordx2 v[92:93], v1, s[28:29]
	s_add_u32 s26, s26, s2
	s_addc_u32 s27, s27, s3
	s_add_u32 s28, s28, s20
	s_addc_u32 s29, s29, s3
	global_load_dword v22, v0, s[26:27]
	global_load_dwordx2 v[94:95], v1, s[28:29]
	s_add_u32 s26, s26, s2
	s_addc_u32 s27, s27, s3
	s_add_u32 s28, s28, s20
	s_addc_u32 s29, s29, s3
	global_load_dword v23, v0, s[26:27]
	global_load_dwordx2 v[96:97], v1, s[28:29]
	s_add_u32 s26, s26, s2
	s_addc_u32 s27, s27, s3
	s_add_u32 s28, s28, s20
	s_addc_u32 s29, s29, s3
; __device__ __forceinline__ unsigned pk2(float lo, float hi) { unsigned r; asm volatile("v_cvt_pk_bf16_f32 %0, %1, %2" : "=v"(r) : "v"(lo), "v"(hi)); return r; }
; __device__ __forceinline__ float bflo(unsigned w) { return __uint_as_float(w << 16); }
; __device__ __forceinline__ float bfhi(unsigned w) { return __uint_as_float(w & 0xffff0000u); }
; __device__ __forceinline__ void gla_scan(bf16_t* __restrict__ UPD, const float* __restrict__ DEC) {
;     ...
;         for (int nb = 0; nb < 256; nb += 8) {
;             if (nb + 8 < 256) {
; #pragma unroll
;                 for (int k = 0; k < 8; ++k) { const int n = dir ? 255 - (nb + 8 + k) : nb + 8 + k; un[k] = up[(size_t)n * 16384]; dn[k] = *(const float2*)(dp + n * 128); }
;             }
; #pragma unroll
;             for (int k = 0; k < 8; ++k) { const int n = dir ? 255 - (nb + k) : nb + k; up[(size_t)n * 16384] = pk2(s0, s1); s0 = dc[k].x * s0 + bflo(uv[k]); s1 = dc[k].y * s1 + bfhi(uv[k]); }
; #pragma unroll
;             for (int k = 0; k < 8; ++k) { uv[k] = un[k]; dc[k] = dn[k]; }
;         }
.Lscan_skipA:
	s_waitcnt vmcnt(48)
	s_cmp_eq_u32 s100, 7
	s_cbranch_scc0 .Lscan_nB
	s_waitcnt vmcnt(16)
.Lscan_nB:
	v_cvt_pk_bf16_f32 v4, v2, v3
	global_store_dword v0, v4, s[0:1]
	s_add_u32 s0, s0, s2
	s_addc_u32 s1, s1, s3
	v_lshlrev_b32_e32 v5, 16, v40
	v_and_b32_e32 v6, 0xffff0000, v40
	v_fma_f32 v2, v98, v2, v5
	v_fma_f32 v3, v99, v3, v6
	v_cvt_pk_bf16_f32 v56, v2, v3
	global_store_dword v0, v56, s[0:1]
	s_add_u32 s0, s0, s2
	s_addc_u32 s1, s1, s3
	v_lshlrev_b32_e32 v57, 16, v41
	v_and_b32_e32 v58, 0xffff0000, v41
	v_fma_f32 v2, v100, v2, v57
	v_fma_f32 v3, v101, v3, v58
	v_cvt_pk_bf16_f32 v4, v2, v3
	global_store_dword v0, v4, s[0:1]
	s_add_u32 s0, s0, s2
	s_addc_u32 s1, s1, s3
	v_lshlrev_b32_e32 v5, 16, v42
	v_and_b32_e32 v6, 0xffff0000, v42
	v_fma_f32 v2, v102, v2, v5
	v_fma_f32 v3, v103, v3, v6
	v_cvt_pk_bf16_f32 v56, v2, v3
	global_store_dword v0, v56, s[0:1]
	s_add_u32 s0, s0, s2
	s_addc_u32 s1, s1, s3
	v_lshlrev_b32_e32 v57, 16, v43
	v_and_b32_e32 v58, 0xffff0000, v43
	v_fma_f32 v2, v104, v2, v57
	v_fma_f32 v3, v105, v3, v58
	v_cvt_pk_bf16_f32 v4, v2, v3
	global_store_dword v0, v4, s[0:1]
	s_add_u32 s0, s0, s2
	s_addc_u32 s1, s1, s3
	v_lshlrev_b32_e32 v5, 16, v44
	v_and_b32_e32 v6, 0xffff0000, v44
	v_fma_f32 v2, v106, v2, v5
	v_fma_f32 v3, v107, v3, v6
	v_cvt_pk_bf16_f32 v56, v2, v3
	global_store_dword v0, v56, s[0:1]
	s_add_u32 s0, s0, s2
	s_addc_u32 s1, s1, s3
	v_lshlrev_b32_e32 v57, 16, v45
	v_and_b32_e32 v58, 0xffff0000, v45
	v_fma_f32 v2, v108, v2, v57
	v_fma_f32 v3, v109, v3, v58
	v_cvt_pk_bf16_f32 v4, v2, v3
	global_store_dword v0, v4, s[0:1]
	s_add_u32 s0, s0, s2
	s_addc_u32 s1, s1, s3
	v_lshlrev_b32_e32 v5, 16, v46
	v_and_b32_e32 v6, 0xffff0000, v46
	v_fma_f32 v2, v110, v2, v5
	v_fma_f32 v3, v111, v3, v6
	v_cvt_pk_bf16_f32 v56, v2, v3
	global_store_dword v0, v56, s[0:1]
	s_add_u32 s0, s0, s2
	s_addc_u32 s1, s1, s3
	v_lshlrev_b32_e32 v57, 16, v47
	v_and_b32_e32 v58, 0xffff0000, v47
	v_fma_f32 v2, v112, v2, v57
	v_fma_f32 v3, v113, v3, v58
	v_cvt_pk_bf16_f32 v4, v2, v3
	global_store_dword v0, v4, s[0:1]
	s_add_u32 s0, s0, s2
	s_addc_u32 s1, s1, s3
	v_lshlrev_b32_e32 v5, 16, v48
	v_and_b32_e32 v6, 0xffff0000, v48
	v_fma_f32 v2, v114, v2, v5
	v_fma_f32 v3, v115, v3, v6
	v_cvt_pk_bf16_f32 v56, v2, v3
	global_store_dword v0, v56, s[0:1]
	s_add_u32 s0, s0, s2
	s_addc_u32 s1, s1, s3
	v_lshlrev_b32_e32 v57, 16, v49
	v_and_b32_e32 v58, 0xffff0000, v49
	v_fma_f32 v2, v116, v2, v57
	v_fma_f32 v3, v117, v3, v58
	v_cvt_pk_bf16_f32 v4, v2, v3
	global_store_dword v0, v4, s[0:1]
	s_add_u32 s0, s0, s2
	s_addc_u32 s1, s1, s3
	v_lshlrev_b32_e32 v5, 16, v50
	v_and_b32_e32 v6, 0xffff0000, v50
	v_fma_f32 v2, v118, v2, v5
	v_fma_f32 v3, v119, v3, v6
	v_cvt_pk_bf16_f32 v56, v2, v3
	global_store_dword v0, v56, s[0:1]
	s_add_u32 s0, s0, s2
	s_addc_u32 s1, s1, s3
	v_lshlrev_b32_e32 v57, 16, v51
	v_and_b32_e32 v58, 0xffff0000, v51
	v_fma_f32 v2, v120, v2, v57
	v_fma_f32 v3, v121, v3, v58
	v_cvt_pk_bf16_f32 v4, v2, v3
	global_store_dword v0, v4, s[0:1]
	s_add_u32 s0, s0, s2
	s_addc_u32 s1, s1, s3
	v_lshlrev_b32_e32 v5, 16, v52
	v_and_b32_e32 v6, 0xffff0000, v52
	v_fma_f32 v2, v122, v2, v5
	v_fma_f32 v3, v123, v3, v6
	v_cvt_pk_bf16_f32 v56, v2, v3
	global_store_dword v0, v56, s[0:1]
	s_add_u32 s0, s0, s2
	s_addc_u32 s1, s1, s3
	v_lshlrev_b32_e32 v57, 16, v53
	v_and_b32_e32 v58, 0xffff0000, v53
	v_fma_f32 v2, v124, v2, v57
	v_fma_f32 v3, v125, v3, v58
	v_cvt_pk_bf16_f32 v4, v2, v3
	global_store_dword v0, v4, s[0:1]
	s_add_u32 s0, s0, s2
	s_addc_u32 s1, s1, s3
	v_lshlrev_b32_e32 v5, 16, v54
	v_and_b32_e32 v6, 0xffff0000, v54
	v_fma_f32 v2, v126, v2, v5
	v_fma_f32 v3, v127, v3, v6
	v_cvt_pk_bf16_f32 v56, v2, v3
	global_store_dword v0, v56, s[0:1]
	s_add_u32 s0, s0, s2
	s_addc_u32 s1, s1, s3
	v_lshlrev_b32_e32 v57, 16, v55
	v_and_b32_e32 v58, 0xffff0000, v55
	v_fma_f32 v2, v128, v2, v57
	v_fma_f32 v3, v129, v3, v58
	s_cmp_eq_u32 s100, 7
	s_cbranch_scc1 .LBB0_287
	global_load_dword v40, v0, s[26:27]
	global_load_dwordx2 v[98:99], v1, s[28:29]
	s_add_u32 s26, s26, s2
	s_addc_u32 s27, s27, s3
	s_add_u32 s28, s28, s20
	s_addc_u32 s29, s29, s3
	global_load_dword v41, v0, s[26:27]
	global_load_dwordx2 v[100:101], v1, s[28:29]
	s_add_u32 s26, s26, s2
	s_addc_u32 s27, s27, s3
	s_add_u32 s28, s28, s20
	s_addc_u32 s29, s29, s3
	global_load_dword v42, v0, s[26:27]
	global_load_dwordx2 v[102:103], v1, s[28:29]
	s_add_u32 s26, s26, s2
	s_addc_u32 s27, s27, s3
	s_add_u32 s28, s28, s20
	s_addc_u32 s29, s29, s3
	global_load_dword v43, v0, s[26:27]
	global_load_dwordx2 v[104:105], v1, s[28:29]
	s_add_u32 s26, s26, s2
	s_addc_u32 s27, s27, s3
	s_add_u32 s28, s28, s20
	s_addc_u32 s29, s29, s3
	global_load_dword v44, v0, s[26:27]
	global_load_dwordx2 v[106:107], v1, s[28:29]
	s_add_u32 s26, s26, s2
	s_addc_u32 s27, s27, s3
	s_add_u32 s28, s28, s20
	s_addc_u32 s29, s29, s3
	global_load_dword v45, v0, s[26:27]
	global_load_dwordx2 v[108:109], v1, s[28:29]
	s_add_u32 s26, s26, s2
	s_addc_u32 s27, s27, s3
	s_add_u32 s28, s28, s20
	s_addc_u32 s29, s29, s3
	global_load_dword v46, v0, s[26:27]
	global_load_dwordx2 v[110:111], v1, s[28:29]
	s_add_u32 s26, s26, s2
	s_addc_u32 s27, s27, s3
	s_add_u32 s28, s28, s20
	s_addc_u32 s29, s29, s3
	global_load_dword v47, v0, s[26:27]
	global_load_dwordx2 v[112:113], v1, s[28:29]
	s_add_u32 s26, s26, s2
	s_addc_u32 s27, s27, s3
	s_add_u32 s28, s28, s20
	s_addc_u32 s29, s29, s3
	global_load_dword v48, v0, s[26:27]
	global_load_dwordx2 v[114:115], v1, s[28:29]
	s_add_u32 s26, s26, s2
	s_addc_u32 s27, s27, s3
	s_add_u32 s28, s28, s20
	s_addc_u32 s29, s29, s3
	global_load_dword v49, v0, s[26:27]
	global_load_dwordx2 v[116:117], v1, s[28:29]
	s_add_u32 s26, s26, s2
	s_addc_u32 s27, s27, s3
	s_add_u32 s28, s28, s20
	s_addc_u32 s29, s29, s3
	global_load_dword v50, v0, s[26:27]
	global_load_dwordx2 v[118:119], v1, s[28:29]
	s_add_u32 s26, s26, s2
	s_addc_u32 s27, s27, s3
	s_add_u32 s28, s28, s20
	s_addc_u32 s29, s29, s3
	global_load_dword v51, v0, s[26:27]
	global_load_dwordx2 v[120:121], v1, s[28:29]
	s_add_u32 s26, s26, s2
	s_addc_u32 s27, s27, s3
	s_add_u32 s28, s28, s20
	s_addc_u32 s29, s29, s3
	global_load_dword v52, v0, s[26:27]
	global_load_dwordx2 v[122:123], v1, s[28:29]
	s_add_u32 s26, s26, s2
	s_addc_u32 s27, s27, s3
	s_add_u32 s28, s28, s20
	s_addc_u32 s29, s29, s3
	global_load_dword v53, v0, s[26:27]
	global_load_dwordx2 v[124:125], v1, s[28:29]
	s_add_u32 s26, s26, s2
	s_addc_u32 s27, s27, s3
	s_add_u32 s28, s28, s20
	s_addc_u32 s29, s29, s3
	global_load_dword v54, v0, s[26:27]
	global_load_dwordx2 v[126:127], v1, s[28:29]
	s_add_u32 s26, s26, s2
	s_addc_u32 s27, s27, s3
	s_add_u32 s28, s28, s20
	s_addc_u32 s29, s29, s3
	global_load_dword v55, v0, s[26:27]
	global_load_dwordx2 v[128:129], v1, s[28:29]
	s_add_u32 s26, s26, s2
	s_addc_u32 s27, s27, s3
	s_add_u32 s28, s28, s20
	s_addc_u32 s29, s29, s3
	s_add_i32 s100, s100, 1
	s_branch .Lscan_loop

; __device__ __forceinline__ void hyena_conv_mfma(const Args& a, int l, int o, unsigned char* sm, const bf16_t* __restrict__ FILT, const u64_t* __restrict__ FSUM,
;                                                 const bf16_t* __restrict__ ZinT, const bf16_t* __restrict__ GT, bf16_t* __restrict__ OutT) {
;     ...
;         bf16x8 R[10];
; #pragma unroll
;         for (int m = 0; m < 6; ++m) R[m] = ld_kfrag(kd, xb + 16 * m, sh);
;         unsigned ra[5], rb[5];
;         { const int dwa = (xb + 16 * 6) >> 1, dwb = (xb + 16 * 7) >> 1;
; #pragma unroll
;           for (int e = 0; e < 5; ++e) { ra[e] = kd[dwa + e]; rb[e] = kd[dwb + e]; } }
;         bf16x8 zr0 = *(const bf16x8*)(zp + zpad(zi0)), zr1 = *(const bf16x8*)(zp + zpad(zi0 - 16 * 128));
;         const int wks = __builtin_amdgcn_readfirstlane(wk);
;         for (int it = 0; it < 64; ++it) {
;             const bool do0 = !(wks == 1 && it >= 51), do1 = !(wks == 0 && it < 12);
; #pragma unroll
;             for (int u = 0; u < 5; ++u) {
;                 const int j = it * 5 + u;
;                 { u32x4 oa, ob;
;                   oa.x = __builtin_amdgcn_alignbit(ra[1], ra[0], sh); oa.y = __builtin_amdgcn_alignbit(ra[2], ra[1], sh); oa.z = __builtin_amdgcn_alignbit(ra[3], ra[2], sh); oa.w = __builtin_amdgcn_alignbit(ra[4], ra[3], sh);
;                   ob.x = __builtin_amdgcn_alignbit(rb[1], rb[0], sh); ob.y = __builtin_amdgcn_alignbit(rb[2], rb[1], sh); ob.z = __builtin_amdgcn_alignbit(rb[3], rb[2], sh); ob.w = __builtin_amdgcn_alignbit(rb[4], rb[3], sh);
;                   R[(2 * u + 6) % 10] = __builtin_bit_cast(bf16x8, oa); R[(2 * u + 7) % 10] = __builtin_bit_cast(bf16x8, ob); }
;                 const bf16x8 zb0 = zr0, zb1 = zr1;
;                 { const int dwa = (xb + 16 * (2 * j + 8)) >> 1, dwb = (xb + 16 * (2 * j + 9)) >> 1;
; #pragma unroll
;                   for (int e = 0; e < 5; ++e) { ra[e] = kd[dwa + e]; rb[e] = kd[dwb + e]; } }
;                 zr0 = *(const bf16x8*)(zp + zpad(zi0 + 32 * (j + 1))); zr1 = *(const bf16x8*)(zp + zpad(zi0 + 32 * (j + 1) - 16 * 128));
;                 __builtin_amdgcn_sched_barrier(0);
;                 if (do0) {
; #pragma unroll
;                     for (int q = 0; q < 8; ++q) acc[q][0] = __builtin_amdgcn_mfma_f32_16x16x32_bf16(R[(2 * u + q) % 10], zb0, acc[q][0], 0, 0, 0);
.LBB0_407:
	s_or_b64 exec, exec, s[2:3]
	s_waitcnt lgkmcnt(0)
	s_barrier
	s_waitcnt vmcnt(0)
	ds_read2_b32 v[4:5], v167 offset0:3 offset1:4
	ds_read2_b32 v[6:7], v167 offset0:32 offset1:33
	ds_read2_b32 v[8:9], v167 offset0:1 offset1:2
	ds_read2_b32 v[10:11], v167 offset1:1
	v_readfirstlane_b32 s3, v152
	s_waitcnt lgkmcnt(3)
	v_alignbit_b32 v73, v5, v4, v3
	v_mov_b32_e32 v64, v65
	s_waitcnt lgkmcnt(1)
	v_alignbit_b32 v72, v4, v9, v2
	s_waitcnt lgkmcnt(0)
	v_alignbit_b32 v71, v9, v11, v1
	v_alignbit_b32 v70, v8, v10, v0
	ds_read2_b32 v[4:5], v168 offset0:3 offset1:4
	ds_read2_b32 v[8:9], v168 offset1:1
	ds_read2_b32 v[10:11], v168 offset0:1 offset1:2
	ds_read2_b32 v[12:13], v169 offset1:1
	ds_read2_b32 v[14:15], v169 offset0:1 offset1:2
	ds_read2_b32 v[16:17], v169 offset0:3 offset1:4
	s_waitcnt lgkmcnt(5)
	v_alignbit_b32 v77, v5, v4, v3
	s_waitcnt lgkmcnt(3)
	v_alignbit_b32 v76, v4, v11, v2
	ds_read2_b32 v[4:5], v167 offset0:33 offset1:34
	ds_read2_b32 v[18:19], v167 offset0:35 offset1:36
	v_alignbit_b32 v75, v11, v9, v1
	v_alignbit_b32 v74, v10, v8, v0
	ds_read2_b32 v[8:9], v170 offset1:1
	ds_read2_b32 v[10:11], v170 offset0:1 offset1:2
	ds_read2_b32 v[20:21], v170 offset0:3 offset1:4
	s_waitcnt lgkmcnt(6)
	v_alignbit_b32 v79, v15, v13, v1
	v_alignbit_b32 v78, v14, v12, v0
	ds_read2_b32 v[12:13], v172 offset1:1
	s_waitcnt lgkmcnt(2)
	v_alignbit_b32 v83, v11, v9, v1
	s_waitcnt lgkmcnt(1)
	v_alignbit_b32 v84, v20, v11, v2
	v_alignbit_b32 v82, v10, v8, v0
	ds_read2_b32 v[8:9], v172 offset0:1 offset1:2
	ds_read2_b32 v[10:11], v172 offset0:3 offset1:4
	ds_read_b32 v94, v155
	ds_read_b32 v124, v156
	ds_read2_b32 v[96:97], v155 offset0:1 offset1:2
	ds_read2_b32 v[98:99], v155 offset0:3 offset1:4
	ds_read2_b32 v[100:101], v156 offset0:1 offset1:2
	ds_read2_b32 v[122:123], v156 offset0:3 offset1:4
	ds_read_b128 v[114:117], v157 offset:8192
	ds_read_b128 v[110:113], v158 offset:8192
	v_alignbit_b32 v81, v17, v16, v3
	v_alignbit_b32 v80, v16, v15, v2
	v_alignbit_b32 v85, v21, v20, v3
	v_alignbit_b32 v89, v19, v18, v3
	v_alignbit_b32 v88, v18, v5, v2
	v_alignbit_b32 v87, v5, v7, v1
	v_alignbit_b32 v86, v4, v6, v0
	s_waitcnt lgkmcnt(8)
	v_alignbit_b32 v93, v11, v10, v3
	v_alignbit_b32 v92, v10, v9, v2
	v_alignbit_b32 v91, v9, v13, v1
	v_alignbit_b32 v90, v8, v12, v0
	s_cmp_lg_u32 s3, 1
	v_mov_b32_e32 v66, v65
	v_mov_b32_e32 v67, v65
	v_mov_b64_e32 v[4:5], v[64:65]
	v_mov_b64_e32 v[8:9], v[64:65]
	v_mov_b64_e32 v[12:13], v[64:65]
	v_mov_b64_e32 v[16:17], v[64:65]
	v_mov_b64_e32 v[20:21], v[64:65]
	v_mov_b64_e32 v[24:25], v[64:65]
	v_mov_b64_e32 v[28:29], v[64:65]
	v_mov_b64_e32 v[32:33], v[64:65]
	v_mov_b64_e32 v[36:37], v[64:65]
	v_mov_b64_e32 v[40:41], v[64:65]
	v_mov_b64_e32 v[44:45], v[64:65]
	v_mov_b64_e32 v[48:49], v[64:65]
	v_mov_b64_e32 v[52:53], v[64:65]
	v_mov_b64_e32 v[56:57], v[64:65]
	v_mov_b64_e32 v[60:61], v[64:65]
	s_cselect_b64 s[56:57], -1, 0
	s_cmp_lg_u32 s3, 0
	v_mov_b64_e32 v[6:7], v[66:67]
	v_mov_b64_e32 v[10:11], v[66:67]
	v_mov_b64_e32 v[14:15], v[66:67]
	v_mov_b64_e32 v[18:19], v[66:67]
	v_mov_b64_e32 v[22:23], v[66:67]
	v_mov_b64_e32 v[26:27], v[66:67]
	v_mov_b64_e32 v[30:31], v[66:67]
	v_mov_b64_e32 v[34:35], v[66:67]
	v_mov_b64_e32 v[38:39], v[66:67]
	v_mov_b64_e32 v[42:43], v[66:67]
	v_mov_b64_e32 v[46:47], v[66:67]
	v_mov_b64_e32 v[50:51], v[66:67]
	v_mov_b64_e32 v[54:55], v[66:67]
	v_mov_b64_e32 v[58:59], v[66:67]
	v_mov_b64_e32 v[62:63], v[66:67]
	v_mov_b64_e32 v[68:69], v[66:67]
	s_mov_b32 s2, 0
	s_cselect_b64 s[58:59], -1, 0
	v_mov_b32_e32 v185, v178
	v_mov_b64_e32 v[66:67], v[64:65]
	s_mov_b32 s3, 0
	v_ashrrev_i32_e32 v201, 7, v179
	v_lshl_add_u32 v185, v201, 4, v185
	v_lshlrev_b32_e32 v201, 1, v180
	v_add_u32_e32 v201, 0x102, v201
	v_and_b32_e32 v201, -4, v201
	s_branch .LBB0_409
.LBB0_408:
	s_add_i32 s3, s3, 1
	s_addk_i32 s2, 0xa0
	s_cmpk_eq_i32 s2, 0x2800
	v_add_u32_e32 v185, 0x140, v185
	v_add_u32_e32 v201, 0x140, v201
	s_cbranch_scc1 .LBB0_429
.LBB0_409:
	s_waitcnt lgkmcnt(8)
	ds_read2_b32 v[102:103], v201 offset1:1
	ds_read2_b32 v[108:109], v201 offset0:1 offset1:2
	ds_read2_b32 v[106:107], v201 offset0:8 offset1:9
	ds_read2_b32 v[126:127], v201 offset0:9 offset1:10
	ds_read2_b32 v[104:105], v201 offset0:3 offset1:4
	ds_read2_b32 v[128:129], v201 offset0:11 offset1:12
	s_add_i32 s100, s2, 0x820
	s_lshr_b32 s100, s100, 7
	s_lshl_b32 s100, s100, 4
	v_add_u32_e32 v118, s100, v185
	s_waitcnt lgkmcnt(11)
	v_alignbit_b32 v94, v96, v94, v0
	v_alignbit_b32 v95, v97, v96, v0
	s_waitcnt lgkmcnt(9)
	v_alignbit_b32 v96, v98, v97, v0
	v_alignbit_b32 v97, v99, v98, v0
	s_waitcnt lgkmcnt(9)
	v_alignbit_b32 v98, v100, v124, v0
	v_alignbit_b32 v99, v101, v100, v0
	s_waitcnt lgkmcnt(8)
	v_alignbit_b32 v100, v122, v101, v0
	v_alignbit_b32 v101, v123, v122, v0
	ds_read_b128 v[122:125], v118 offset:4352
	ds_read_b128 v[118:121], v118
	s_cmp_lt_u32 s3, 51
	s_cselect_b64 s[26:27], -1, 0
	s_or_b64 s[28:29], s[56:57], s[26:27]
	v_cndmask_b32_e64 v202, 0, 1, s[28:29]
	v_cmp_ne_u32_e64 s[26:27], 1, v202
	s_andn2_b64 vcc, exec, s[28:29]
	s_cbranch_vccnz .LBB0_411
	s_waitcnt lgkmcnt(9)
	v_mfma_f32_16x16x32_bf16 v[66:69], v[70:73], v[114:117], v[66:69]
	v_mfma_f32_16x16x32_bf16 v[56:59], v[74:77], v[114:117], v[56:59]
	v_mfma_f32_16x16x32_bf16 v[48:51], v[78:81], v[114:117], v[48:51]
	v_mfma_f32_16x16x32_bf16 v[40:43], v[82:85], v[114:117], v[40:43]
	v_mfma_f32_16x16x32_bf16 v[32:35], v[86:89], v[114:117], v[32:35]
	v_mfma_f32_16x16x32_bf16 v[24:27], v[90:93], v[114:117], v[24:27]
	v_mfma_f32_16x16x32_bf16 v[16:19], v[94:97], v[114:117], v[16:19]
	v_mfma_f32_16x16x32_bf16 v[8:11], v[98:101], v[114:117], v[8:11]

; __device__ __forceinline__ void hyena_conv_mfma(const Args& a, int l, int o, unsigned char* sm, const bf16_t* __restrict__ FILT, const u64_t* __restrict__ FSUM,
;                                                 const bf16_t* __restrict__ ZinT, const bf16_t* __restrict__ GT, bf16_t* __restrict__ OutT) {
;     ...
;             for (int u = 0; u < 5; ++u) {
;                 const int j = it * 5 + u;
;                 { u32x4 oa, ob;
;                   oa.x = __builtin_amdgcn_alignbit(ra[1], ra[0], sh); oa.y = __builtin_amdgcn_alignbit(ra[2], ra[1], sh); oa.z = __builtin_amdgcn_alignbit(ra[3], ra[2], sh); oa.w = __builtin_amdgcn_alignbit(ra[4], ra[3], sh);
;                   ob.x = __builtin_amdgcn_alignbit(rb[1], rb[0], sh); ob.y = __builtin_amdgcn_alignbit(rb[2], rb[1], sh); ob.z = __builtin_amdgcn_alignbit(rb[3], rb[2], sh); ob.w = __builtin_amdgcn_alignbit(rb[4], rb[3], sh);
;                   R[(2 * u + 6) % 10] = __builtin_bit_cast(bf16x8, oa); R[(2 * u + 7) % 10] = __builtin_bit_cast(bf16x8, ob); }
;                 const bf16x8 zb0 = zr0, zb1 = zr1;
;                 { const int dwa = (xb + 16 * (2 * j + 8)) >> 1, dwb = (xb + 16 * (2 * j + 9)) >> 1;
; #pragma unroll
;                   for (int e = 0; e < 5; ++e) { ra[e] = kd[dwa + e]; rb[e] = kd[dwb + e]; } }
;                 zr0 = *(const bf16x8*)(zp + zpad(zi0 + 32 * (j + 1))); zr1 = *(const bf16x8*)(zp + zpad(zi0 + 32 * (j + 1) - 16 * 128));
.LBB0_413:
	s_waitcnt lgkmcnt(8)
	ds_read2_b32 v[70:71], v201 offset0:16 offset1:17
	ds_read2_b32 v[76:77], v201 offset0:17 offset1:18
	ds_read2_b32 v[74:75], v201 offset0:24 offset1:25
	ds_read2_b32 v[114:115], v201 offset0:25 offset1:26
	ds_read2_b32 v[72:73], v201 offset0:19 offset1:20
	ds_read2_b32 v[116:117], v201 offset0:27 offset1:28
	s_add_i32 s100, s2, 0x840
	s_lshr_b32 s100, s100, 7
	s_lshl_b32 s100, s100, 4
	v_add_u32_e32 v110, s100, v185
	s_waitcnt lgkmcnt(9)
	v_alignbit_b32 v105, v105, v104, v3
	v_alignbit_b32 v104, v104, v109, v2
	v_alignbit_b32 v103, v109, v103, v1
	v_alignbit_b32 v102, v108, v102, v0
	s_waitcnt lgkmcnt(8)
	v_alignbit_b32 v109, v129, v128, v3
	v_alignbit_b32 v108, v128, v127, v2
	v_alignbit_b32 v107, v127, v107, v1
	v_alignbit_b32 v106, v126, v106, v0
	ds_read_b128 v[126:129], v110 offset:4416
	ds_read_b128 v[110:113], v110 offset:64
	s_and_b64 vcc, exec, s[26:27]
	s_cbranch_vccnz .LBB0_415
	s_waitcnt lgkmcnt(9)
	v_mfma_f32_16x16x32_bf16 v[66:69], v[78:81], v[122:125], v[66:69]
	v_mfma_f32_16x16x32_bf16 v[56:59], v[82:85], v[122:125], v[56:59]
	v_mfma_f32_16x16x32_bf16 v[48:51], v[86:89], v[122:125], v[48:51]
	v_mfma_f32_16x16x32_bf16 v[40:43], v[90:93], v[122:125], v[40:43]
	v_mfma_f32_16x16x32_bf16 v[32:35], v[94:97], v[122:125], v[32:35]
	v_mfma_f32_16x16x32_bf16 v[24:27], v[98:101], v[122:125], v[24:27]
	v_mfma_f32_16x16x32_bf16 v[16:19], v[102:105], v[122:125], v[16:19]
	v_mfma_f32_16x16x32_bf16 v[8:11], v[106:109], v[122:125], v[8:11]

; __device__ __forceinline__ void hyena_conv_mfma(const Args& a, int l, int o, unsigned char* sm, const bf16_t* __restrict__ FILT, const u64_t* __restrict__ FSUM,
;                                                 const bf16_t* __restrict__ ZinT, const bf16_t* __restrict__ GT, bf16_t* __restrict__ OutT) {
;     ...
;             for (int u = 0; u < 5; ++u) {
;                 const int j = it * 5 + u;
;                 { u32x4 oa, ob;
;                   oa.x = __builtin_amdgcn_alignbit(ra[1], ra[0], sh); oa.y = __builtin_amdgcn_alignbit(ra[2], ra[1], sh); oa.z = __builtin_amdgcn_alignbit(ra[3], ra[2], sh); oa.w = __builtin_amdgcn_alignbit(ra[4], ra[3], sh);
;                   ob.x = __builtin_amdgcn_alignbit(rb[1], rb[0], sh); ob.y = __builtin_amdgcn_alignbit(rb[2], rb[1], sh); ob.z = __builtin_amdgcn_alignbit(rb[3], rb[2], sh); ob.w = __builtin_amdgcn_alignbit(rb[4], rb[3], sh);
;                   R[(2 * u + 6) % 10] = __builtin_bit_cast(bf16x8, oa); R[(2 * u + 7) % 10] = __builtin_bit_cast(bf16x8, ob); }
;                 const bf16x8 zb0 = zr0, zb1 = zr1;
;                 { const int dwa = (xb + 16 * (2 * j + 8)) >> 1, dwb = (xb + 16 * (2 * j + 9)) >> 1;
; #pragma unroll
;                   for (int e = 0; e < 5; ++e) { ra[e] = kd[dwa + e]; rb[e] = kd[dwb + e]; } }
;                 zr0 = *(const bf16x8*)(zp + zpad(zi0 + 32 * (j + 1))); zr1 = *(const bf16x8*)(zp + zpad(zi0 + 32 * (j + 1) - 16 * 128));
.LBB0_417:
	s_waitcnt lgkmcnt(4)
	v_alignbit_b32 v74, v114, v74, v0
	ds_read2_b32 v[78:79], v201 offset0:32 offset1:33
	ds_read2_b32 v[84:85], v201 offset0:33 offset1:34
	ds_read2_b32 v[82:83], v201 offset0:40 offset1:41
	ds_read2_b32 v[118:119], v201 offset0:41 offset1:42
	ds_read2_b32 v[80:81], v201 offset0:35 offset1:36
	ds_read2_b32 v[120:121], v201 offset0:43 offset1:44
	s_add_i32 s100, s2, 0x860
	s_lshr_b32 s100, s100, 7
	s_lshl_b32 s100, s100, 4
	v_add_u32_e32 v114, s100, v185
	ds_read_b128 v[122:125], v114 offset:4480
	s_waitcnt lgkmcnt(10)
	v_alignbit_b32 v73, v73, v72, v3
	v_alignbit_b32 v72, v72, v77, v2
	v_alignbit_b32 v71, v77, v71, v1
	v_alignbit_b32 v70, v76, v70, v0
	s_waitcnt lgkmcnt(9)
	v_alignbit_b32 v77, v117, v116, v3
	v_alignbit_b32 v76, v116, v115, v2
	v_alignbit_b32 v75, v115, v75, v1
	ds_read_b128 v[114:117], v114 offset:128
	s_and_b64 vcc, exec, s[26:27]
	s_cbranch_vccnz .LBB0_419
	s_waitcnt lgkmcnt(9)
	v_mfma_f32_16x16x32_bf16 v[66:69], v[86:89], v[126:129], v[66:69]
	v_mfma_f32_16x16x32_bf16 v[56:59], v[90:93], v[126:129], v[56:59]
	v_mfma_f32_16x16x32_bf16 v[48:51], v[94:97], v[126:129], v[48:51]
	v_mfma_f32_16x16x32_bf16 v[40:43], v[98:101], v[126:129], v[40:43]
	v_mfma_f32_16x16x32_bf16 v[32:35], v[102:105], v[126:129], v[32:35]
	v_mfma_f32_16x16x32_bf16 v[24:27], v[106:109], v[126:129], v[24:27]
	v_mfma_f32_16x16x32_bf16 v[16:19], v[70:73], v[126:129], v[16:19]
	v_mfma_f32_16x16x32_bf16 v[8:11], v[74:77], v[126:129], v[8:11]

; __device__ __forceinline__ void hyena_conv_mfma(const Args& a, int l, int o, unsigned char* sm, const bf16_t* __restrict__ FILT, const u64_t* __restrict__ FSUM,
;                                                 const bf16_t* __restrict__ ZinT, const bf16_t* __restrict__ GT, bf16_t* __restrict__ OutT) {
;     ...
;             for (int u = 0; u < 5; ++u) {
;                 const int j = it * 5 + u;
;                 { u32x4 oa, ob;
;                   oa.x = __builtin_amdgcn_alignbit(ra[1], ra[0], sh); oa.y = __builtin_amdgcn_alignbit(ra[2], ra[1], sh); oa.z = __builtin_amdgcn_alignbit(ra[3], ra[2], sh); oa.w = __builtin_amdgcn_alignbit(ra[4], ra[3], sh);
;                   ob.x = __builtin_amdgcn_alignbit(rb[1], rb[0], sh); ob.y = __builtin_amdgcn_alignbit(rb[2], rb[1], sh); ob.z = __builtin_amdgcn_alignbit(rb[3], rb[2], sh); ob.w = __builtin_amdgcn_alignbit(rb[4], rb[3], sh);
;                   R[(2 * u + 6) % 10] = __builtin_bit_cast(bf16x8, oa); R[(2 * u + 7) % 10] = __builtin_bit_cast(bf16x8, ob); }
;                 const bf16x8 zb0 = zr0, zb1 = zr1;
;                 { const int dwa = (xb + 16 * (2 * j + 8)) >> 1, dwb = (xb + 16 * (2 * j + 9)) >> 1;
; #pragma unroll
;                   for (int e = 0; e < 5; ++e) { ra[e] = kd[dwa + e]; rb[e] = kd[dwb + e]; } }
;                 zr0 = *(const bf16x8*)(zp + zpad(zi0 + 32 * (j + 1))); zr1 = *(const bf16x8*)(zp + zpad(zi0 + 32 * (j + 1) - 16 * 128));
.LBB0_421:
	s_waitcnt lgkmcnt(4)
	v_alignbit_b32 v82, v118, v82, v0
	s_add_i32 s100, s2, 0x880
	s_lshr_b32 s100, s100, 7
	s_lshl_b32 s100, s100, 4
	v_add_u32_e32 v118, s100, v185
	ds_read2_b32 v[86:87], v201 offset0:48 offset1:49
	ds_read2_b32 v[92:93], v201 offset0:49 offset1:50
	ds_read2_b32 v[90:91], v201 offset0:56 offset1:57
	ds_read2_b32 v[110:111], v201 offset0:57 offset1:58
	ds_read2_b32 v[88:89], v201 offset0:51 offset1:52
	ds_read2_b32 v[112:113], v201 offset0:59 offset1:60
	ds_read_b128 v[126:129], v118 offset:4544
	s_waitcnt lgkmcnt(10)
	v_alignbit_b32 v81, v81, v80, v3
	v_alignbit_b32 v80, v80, v85, v2
	v_alignbit_b32 v79, v85, v79, v1
	v_alignbit_b32 v78, v84, v78, v0
	s_waitcnt lgkmcnt(9)
	v_alignbit_b32 v85, v121, v120, v3
	v_alignbit_b32 v84, v120, v119, v2
	v_alignbit_b32 v83, v119, v83, v1
	ds_read_b128 v[118:121], v118 offset:192
	s_and_b64 vcc, exec, s[26:27]
	s_cbranch_vccnz .LBB0_423
	s_waitcnt lgkmcnt(9)
	v_mfma_f32_16x16x32_bf16 v[66:69], v[94:97], v[122:125], v[66:69]
	v_mfma_f32_16x16x32_bf16 v[56:59], v[98:101], v[122:125], v[56:59]
	v_mfma_f32_16x16x32_bf16 v[48:51], v[102:105], v[122:125], v[48:51]
	v_mfma_f32_16x16x32_bf16 v[40:43], v[106:109], v[122:125], v[40:43]
	v_mfma_f32_16x16x32_bf16 v[32:35], v[70:73], v[122:125], v[32:35]
	v_mfma_f32_16x16x32_bf16 v[24:27], v[74:77], v[122:125], v[24:27]
	v_mfma_f32_16x16x32_bf16 v[16:19], v[78:81], v[122:125], v[16:19]
	v_mfma_f32_16x16x32_bf16 v[8:11], v[82:85], v[122:125], v[8:11]

; __device__ __forceinline__ void hyena_conv_mfma(const Args& a, int l, int o, unsigned char* sm, const bf16_t* __restrict__ FILT, const u64_t* __restrict__ FSUM,
;                                                 const bf16_t* __restrict__ ZinT, const bf16_t* __restrict__ GT, bf16_t* __restrict__ OutT) {
;     ...
;             for (int u = 0; u < 5; ++u) {
;                 const int j = it * 5 + u;
;                 { u32x4 oa, ob;
;                   oa.x = __builtin_amdgcn_alignbit(ra[1], ra[0], sh); oa.y = __builtin_amdgcn_alignbit(ra[2], ra[1], sh); oa.z = __builtin_amdgcn_alignbit(ra[3], ra[2], sh); oa.w = __builtin_amdgcn_alignbit(ra[4], ra[3], sh);
;                   ob.x = __builtin_amdgcn_alignbit(rb[1], rb[0], sh); ob.y = __builtin_amdgcn_alignbit(rb[2], rb[1], sh); ob.z = __builtin_amdgcn_alignbit(rb[3], rb[2], sh); ob.w = __builtin_amdgcn_alignbit(rb[4], rb[3], sh);
;                   R[(2 * u + 6) % 10] = __builtin_bit_cast(bf16x8, oa); R[(2 * u + 7) % 10] = __builtin_bit_cast(bf16x8, ob); }
;                 const bf16x8 zb0 = zr0, zb1 = zr1;
;                 { const int dwa = (xb + 16 * (2 * j + 8)) >> 1, dwb = (xb + 16 * (2 * j + 9)) >> 1;
; #pragma unroll
;                   for (int e = 0; e < 5; ++e) { ra[e] = kd[dwa + e]; rb[e] = kd[dwb + e]; } }
;                 zr0 = *(const bf16x8*)(zp + zpad(zi0 + 32 * (j + 1))); zr1 = *(const bf16x8*)(zp + zpad(zi0 + 32 * (j + 1) - 16 * 128));
.LBB0_425:
	s_waitcnt lgkmcnt(4)
	v_alignbit_b32 v90, v110, v90, v0
	ds_read_b32 v94, v201 offset:256
	ds_read_b32 v124, v201 offset:288
	ds_read2_b32 v[96:97], v201 offset0:65 offset1:66
	ds_read2_b32 v[100:101], v201 offset0:73 offset1:74
	ds_read2_b32 v[98:99], v201 offset0:67 offset1:68
	ds_read2_b32 v[122:123], v201 offset0:75 offset1:76
	s_add_i32 s100, s2, 0x8a0
	s_lshr_b32 s100, s100, 7
	s_lshl_b32 s100, s100, 4
	v_add_u32_e32 v95, s100, v185
	s_waitcnt lgkmcnt(9)
	v_alignbit_b32 v89, v89, v88, v3
	v_alignbit_b32 v88, v88, v93, v2
	v_alignbit_b32 v87, v93, v87, v1
	v_alignbit_b32 v86, v92, v86, v0
	s_waitcnt lgkmcnt(8)
	v_alignbit_b32 v93, v113, v112, v3
	v_alignbit_b32 v92, v112, v111, v2
	v_alignbit_b32 v91, v111, v91, v1
	ds_read_b128 v[114:117], v95 offset:4608
	ds_read_b128 v[110:113], v95 offset:256
	s_and_b64 vcc, exec, s[26:27]
	s_cbranch_vccnz .LBB0_427
	s_waitcnt lgkmcnt(9)
	v_mfma_f32_16x16x32_bf16 v[66:69], v[102:105], v[126:129], v[66:69]
	v_mfma_f32_16x16x32_bf16 v[56:59], v[106:109], v[126:129], v[56:59]
	v_mfma_f32_16x16x32_bf16 v[48:51], v[70:73], v[126:129], v[48:51]
	v_mfma_f32_16x16x32_bf16 v[40:43], v[74:77], v[126:129], v[40:43]
	v_mfma_f32_16x16x32_bf16 v[32:35], v[78:81], v[126:129], v[32:35]
	v_mfma_f32_16x16x32_bf16 v[24:27], v[82:85], v[126:129], v[24:27]
	v_mfma_f32_16x16x32_bf16 v[16:19], v[86:89], v[126:129], v[16:19]
	v_mfma_f32_16x16x32_bf16 v[8:11], v[90:93], v[126:129], v[8:11]

; __device__ __forceinline__ float bf2f(bf16_t v) { return __uint_as_float(((unsigned)v) << 16); }
; __device__ __forceinline__ int ltid() { int t = threadIdx.x; asm volatile("" : "+v"(t)); return t; }
; __device__ __forceinline__ void gla_b(const Args& a, int l, int hd, int dir, int t0, unsigned char* sm, const bf16_t* __restrict__ PLR) {
;     float* Gb = (float*)(sm + G_GB); float* W2s = (float*)(sm + G_W2); float* Bs = (float*)(sm + G_BS); float* lrs = (float*)(sm + G_LR); float* tot = (float*)(sm + G_TOT);
;     const int tid = ltid();
;     const float* w2 = a.in[18] + ((size_t)(l * 2 + dir) * 16) * 512 + hd * 128;
;     for (int i = tid; i < 2048; i += 512) W2s[i] = w2[(i >> 7) * 512 + (i & 127)];
;     if (tid < 128) Bs[tid] = a.in[19][(l * 2 + dir) * 512 + hd * 128 + tid];
;     for (int i = tid; i < 1024; i += 512) { const int j = i >> 4, r = i & 15; lrs[i] = bf2f(PLR[(size_t)(t0 + j) * 256 + dir * 16 + r]); }
;     __syncthreads();
;     const int d = tid & 127, q = tid >> 7;
;     float run = 0.f;
;     for (int k = 0; k < 16; ++k) {
;         const int s = q * 16 + k, j = dir ? 63 - s : s;
;         float x = Bs[d];
; #pragma unroll
;         for (int r = 0; r < 16; ++r) x += lrs[j * 16 + r] * W2s[r * 128 + d];
; __device__ __forceinline__ void gla_c3(const Args& a, int l, unsigned char* sm, const bf16_t* __restrict__ PC, const bf16_t* __restrict__ PLR, const bf16_t* __restrict__ UPD, bf16_t* __restrict__ OC) {
;     ...
;             const bf16_t* Sg = UPD + ((size_t)((dir * 4 + hd) * 256 + n)) * 32768;
;             bf16x8 sfr[8];
; #pragma unroll
;             for (int ks = 0; ks < 8; ++ks) sfr[ks] = *(const bf16x8*)(Sg + (32 * wid + r) * 128 + ks * 16 + 8 * h);
;             u32x4 qraw[2], kraw[2];
;             { const bf16_t* qp = PC + (size_t)(t0 + (tid >> 3)) * 3072 + hd * 128 + (tid & 7) * 16;
;               qraw[0] = *(const u32x4*)qp; qraw[1] = *(const u32x4*)(qp + 8); kraw[0] = *(const u32x4*)(qp + 512); kraw[1] = *(const u32x4*)(qp + 520); }
;             gla_b(a, l, hd, dir, t0, sm, PLR);
.LBB0_456:
	s_lshl_b32 s2, s47, 10
	s_add_i32 s2, s2, s20
	s_ashr_i32 s3, s2, 31
	s_lshl_b64 s[2:3], s[2:3], 16
	v_lshl_add_u64 v[32:33], v[82:83], 0, s[2:3]
	global_load_dwordx4 v[78:81], v[32:33], off
	global_load_dwordx4 v[74:77], v[32:33], off offset:32
	global_load_dwordx4 v[70:73], v[32:33], off offset:64
	global_load_dwordx4 v[66:69], v[32:33], off offset:96
	global_load_dwordx4 v[60:63], v[32:33], off offset:128
	global_load_dwordx4 v[56:59], v[32:33], off offset:160
	global_load_dwordx4 v[52:55], v[32:33], off offset:192
	global_load_dwordx4 v[48:51], v[32:33], off offset:224
	v_readlane_b32 s2, v246, 35
	v_readlane_b32 s6, v247, 3
	v_readlane_b32 s7, v247, 4
	v_readlane_b32 s34, v246, 13
	v_readlane_b32 s35, v246, 14
	s_nop 3
	s_or_b32 s4, s47, s2
	s_lshl_b32 s2, s4, 15
	s_add_u32 s30, s27, s2
	s_addc_u32 s31, s45, 0
	s_lshl_b32 s2, s4, 9
	s_add_i32 s2, s2, s26
	s_lshl_b32 s2, s2, 2
	s_add_u32 s6, s6, s2
	s_addc_u32 s7, s7, 0
	s_lshl_b32 s2, s47, 5
	s_add_u32 s34, s34, s2
	s_addc_u32 s35, s35, 0
	s_lshl_b32 s2, s44, 9
	s_add_u32 s34, s34, s2
	s_addc_u32 s35, s35, 0
	v_and_b32_e32 v32, 0x7f, v171
	v_lshlrev_b32_e32 v32, 2, v32
	v_lshlrev_b32_e32 v33, 2, v171
	v_lshrrev_b32_e32 v34, 4, v171
	v_lshlrev_b32_e32 v34, 9, v34
	v_and_b32_e32 v35, 15, v171
	v_lshl_or_b32 v34, v35, 1, v34
	v_add_u32_e32 v35, 0x4000, v34
	global_load_ushort v36, v34, s[34:35]
	global_load_ushort v37, v35, s[34:35]
	global_load_dword v38, v32, s[6:7]
	global_load_dword v201, v32, s[30:31]
	global_load_dword v202, v32, s[30:31] offset:2048
	s_add_u32 s30, s30, 0x1000
	s_addc_u32 s31, s31, 0
	global_load_dword v203, v32, s[30:31]
	global_load_dword v204, v32, s[30:31] offset:2048
	s_add_u32 s30, s30, 0x1000
	s_addc_u32 s31, s31, 0
	global_load_dword v205, v32, s[30:31]
	global_load_dword v206, v32, s[30:31] offset:2048
	s_add_u32 s30, s30, 0x1000
	s_addc_u32 s31, s31, 0
	global_load_dword v207, v32, s[30:31]
	global_load_dword v208, v32, s[30:31] offset:2048
	s_add_u32 s30, s30, 0x1000
	s_addc_u32 s31, s31, 0
	global_load_dword v209, v32, s[30:31]
	global_load_dword v210, v32, s[30:31] offset:2048
	s_add_u32 s30, s30, 0x1000
	s_addc_u32 s31, s31, 0
	global_load_dword v211, v32, s[30:31]
	global_load_dword v212, v32, s[30:31] offset:2048
	s_add_u32 s30, s30, 0x1000
	s_addc_u32 s31, s31, 0
	global_load_dword v213, v32, s[30:31]
	global_load_dword v214, v32, s[30:31] offset:2048
	s_add_u32 s30, s30, 0x1000
	s_addc_u32 s31, s31, 0
	global_load_dword v215, v32, s[30:31]
	global_load_dword v216, v32, s[30:31] offset:2048
	s_waitcnt vmcnt(17)
	v_lshlrev_b32_e32 v36, 16, v36
	v_lshlrev_b32_e32 v37, 16, v37
	ds_write_b32 v33, v36 offset:41728
	ds_write_b32 v33, v37 offset:43776
	s_waitcnt lgkmcnt(0)
	s_barrier
	v_lshrrev_b32_e32 v39, 7, v171
	v_lshlrev_b32_e32 v39, 4, v39
	v_sub_u32_e32 v40, 63, v39
	s_cmp_eq_u32 s47, 0
	s_cselect_b32 s3, 64, 0xffffffc0
	s_movk_i32 s101, 0x204
	s_cselect_b32 s101, s101, 0xfffffdfc
	v_cndmask_b32_e64 v39, v40, v39, s[28:29]
	v_lshlrev_b32_e32 v143, 6, v39
	v_add_u32_e32 v143, 0xa300, v143
	v_add_u32_e32 v144, s3, v143
	v_mul_u32_u24_e32 v40, 0x204, v39
	v_add_u32_e32 v40, v40, v32
	s_lshl_b32 s100, s3, 1
	ds_read_b128 v[172:175], v143
	ds_read_b128 v[176:179], v143 offset:16
	ds_read_b128 v[180:183], v143 offset:32
	ds_read_b128 v[164:167], v143 offset:48
	ds_read_b128 v[228:231], v144
	ds_read_b128 v[232:235], v144 offset:16
	ds_read_b128 v[236:239], v144 offset:32
	ds_read_b128 v[240:243], v144 offset:48
	s_mov_b32 s2, 0x3d800000
	s_waitcnt vmcnt(0)
	s_waitcnt lgkmcnt(0)
	v_mov_b32_e32 v141, v38
	v_mov_b32_e32 v142, v38
	v_fmac_f32_e32 v141, v172, v201
	v_fmac_f32_e32 v142, v228, v201
	v_fmac_f32_e32 v141, v173, v202
	v_fmac_f32_e32 v142, v229, v202
	v_fmac_f32_e32 v141, v174, v203
	v_fmac_f32_e32 v142, v230, v203
	v_fmac_f32_e32 v141, v175, v204
	v_fmac_f32_e32 v142, v231, v204
	v_fmac_f32_e32 v141, v176, v205
	v_fmac_f32_e32 v142, v232, v205
	v_fmac_f32_e32 v141, v177, v206
	v_fmac_f32_e32 v142, v233, v206
	v_fmac_f32_e32 v141, v178, v207
	v_fmac_f32_e32 v142, v234, v207
	v_fmac_f32_e32 v141, v179, v208
	v_fmac_f32_e32 v142, v235, v208
	v_fmac_f32_e32 v141, v180, v209
	v_fmac_f32_e32 v142, v236, v209
	v_fmac_f32_e32 v141, v181, v210
	v_fmac_f32_e32 v142, v237, v210
	v_fmac_f32_e32 v141, v182, v211
	v_fmac_f32_e32 v142, v238, v211
	v_fmac_f32_e32 v141, v183, v212
	v_fmac_f32_e32 v142, v239, v212
	v_fmac_f32_e32 v141, v164, v213
	v_fmac_f32_e32 v142, v240, v213
	v_fmac_f32_e32 v141, v165, v214
	v_fmac_f32_e32 v142, v241, v214
	v_fmac_f32_e32 v141, v166, v215
	v_fmac_f32_e32 v142, v242, v215
	v_fmac_f32_e32 v141, v167, v216
	v_fmac_f32_e32 v142, v243, v216
	v_add_u32_e32 v143, s100, v143
	v_add_u32_e32 v144, s100, v144
	ds_read_b128 v[172:175], v143
	ds_read_b128 v[176:179], v143 offset:16
	ds_read_b128 v[180:183], v143 offset:32
	ds_read_b128 v[164:167], v143 offset:48
	ds_read_b128 v[228:231], v144
	ds_read_b128 v[232:235], v144 offset:16
	ds_read_b128 v[236:239], v144 offset:32
	ds_read_b128 v[240:243], v144 offset:48
	v_mul_f32_e64 v41, |v141|, s61
	v_mul_f32_e64 v42, |v142|, s61
	v_exp_f32_e32 v41, v41
	v_exp_f32_e32 v42, v42
	v_min_f32_e32 v43, 0, v141
	v_min_f32_e32 v44, 0, v142
	v_add_f32_e32 v41, 1.0, v41
	v_add_f32_e32 v42, 1.0, v42
	v_cmp_gt_f32_e64 s[4:5], s24, v41
	v_cmp_gt_f32_e64 s[6:7], s24, v42
	s_nop 1
	v_cndmask_b32_e64 v45, 0, 32, s[4:5]
	v_cndmask_b32_e64 v46, 0, 32, s[6:7]
	v_ldexp_f32 v41, v41, v45
	v_ldexp_f32 v42, v42, v46
	v_log_f32_e32 v41, v41
	v_log_f32_e32 v42, v42
	v_cndmask_b32_e64 v45, 0, v192, s[4:5]
	v_cndmask_b32_e64 v46, 0, v192, s[6:7]
	v_mul_f32_e32 v47, 0x3f317217, v41
	v_mul_f32_e32 v140, 0x3f317217, v42
	v_fma_f32 v47, v41, s62, -v47
	v_fma_f32 v140, v42, s62, -v140
	v_fmac_f32_e32 v47, 0x3377d1cf, v41
	v_fmac_f32_e32 v140, 0x3377d1cf, v42
	v_fmac_f32_e32 v47, 0x3f317217, v41
	v_fmac_f32_e32 v140, 0x3f317217, v42
	v_cmp_lt_f32_e64 s[30:31], |v41|, s63
	v_cmp_lt_f32_e64 s[34:35], |v42|, s63
	s_nop 1
	v_cndmask_b32_e64 v41, v41, v47, s[30:31]
	v_cndmask_b32_e64 v42, v42, v140, s[34:35]
	v_sub_f32_e32 v41, v41, v45
	v_sub_f32_e32 v42, v42, v46
	v_sub_f32_e32 v41, v43, v41
	v_sub_f32_e32 v42, v44, v42
	v_fma_f32 v217, v41, s2, v65
	v_fma_f32 v218, v42, s2, v217
	s_waitcnt lgkmcnt(0)
; __device__ __forceinline__ void gla_b(const Args& a, int l, int hd, int dir, int t0, unsigned char* sm, const bf16_t* __restrict__ PLR) {
;     ...
;     for (int k = 0; k < 16; ++k) {
;         const int s = q * 16 + k, j = dir ? 63 - s : s;
;         float x = Bs[d];
; #pragma unroll
;         for (int r = 0; r < 16; ++r) x += lrs[j * 16 + r] * W2s[r * 128 + d];
;         const float g = (fminf(x, 0.f) - __logf(1.f + __expf(-fabsf(x)))) * (1.f / 16.f);
;         run += g; Gb[j * 129 + d] = run;
;     }
	v_mov_b32_e32 v141, v38
	v_mov_b32_e32 v142, v38
	v_fmac_f32_e32 v141, v172, v201
	v_fmac_f32_e32 v142, v228, v201
	v_fmac_f32_e32 v141, v173, v202
	v_fmac_f32_e32 v142, v229, v202
	v_fmac_f32_e32 v141, v174, v203
	v_fmac_f32_e32 v142, v230, v203
	v_fmac_f32_e32 v141, v175, v204
	v_fmac_f32_e32 v142, v231, v204
	v_fmac_f32_e32 v141, v176, v205
	v_fmac_f32_e32 v142, v232, v205
	v_fmac_f32_e32 v141, v177, v206
	v_fmac_f32_e32 v142, v233, v206
	v_fmac_f32_e32 v141, v178, v207
	v_fmac_f32_e32 v142, v234, v207
	v_fmac_f32_e32 v141, v179, v208
	v_fmac_f32_e32 v142, v235, v208
	v_fmac_f32_e32 v141, v180, v209
	v_fmac_f32_e32 v142, v236, v209
	v_fmac_f32_e32 v141, v181, v210
	v_fmac_f32_e32 v142, v237, v210
	v_fmac_f32_e32 v141, v182, v211
	v_fmac_f32_e32 v142, v238, v211
	v_fmac_f32_e32 v141, v183, v212
	v_fmac_f32_e32 v142, v239, v212
	v_fmac_f32_e32 v141, v164, v213
	v_fmac_f32_e32 v142, v240, v213
	v_fmac_f32_e32 v141, v165, v214
	v_fmac_f32_e32 v142, v241, v214
	v_fmac_f32_e32 v141, v166, v215
	v_fmac_f32_e32 v142, v242, v215
	v_fmac_f32_e32 v141, v167, v216
	v_fmac_f32_e32 v142, v243, v216
	v_add_u32_e32 v143, s100, v143
	v_add_u32_e32 v144, s100, v144
	ds_read_b128 v[172:175], v143
	ds_read_b128 v[176:179], v143 offset:16
	ds_read_b128 v[180:183], v143 offset:32
	ds_read_b128 v[164:167], v143 offset:48
	ds_read_b128 v[228:231], v144
	ds_read_b128 v[232:235], v144 offset:16
	ds_read_b128 v[236:239], v144 offset:32
	ds_read_b128 v[240:243], v144 offset:48
	v_mul_f32_e64 v41, |v141|, s61
	v_mul_f32_e64 v42, |v142|, s61
	v_exp_f32_e32 v41, v41
	v_exp_f32_e32 v42, v42
	v_min_f32_e32 v43, 0, v141
	v_min_f32_e32 v44, 0, v142
	v_add_f32_e32 v41, 1.0, v41
	v_add_f32_e32 v42, 1.0, v42
	v_cmp_gt_f32_e64 s[4:5], s24, v41
	v_cmp_gt_f32_e64 s[6:7], s24, v42
	s_nop 1
	v_cndmask_b32_e64 v45, 0, 32, s[4:5]
	v_cndmask_b32_e64 v46, 0, 32, s[6:7]
	v_ldexp_f32 v41, v41, v45
	v_ldexp_f32 v42, v42, v46
	v_log_f32_e32 v41, v41
	v_log_f32_e32 v42, v42
	v_cndmask_b32_e64 v45, 0, v192, s[4:5]
	v_cndmask_b32_e64 v46, 0, v192, s[6:7]
	v_mul_f32_e32 v47, 0x3f317217, v41
	v_mul_f32_e32 v140, 0x3f317217, v42
	v_fma_f32 v47, v41, s62, -v47
	v_fma_f32 v140, v42, s62, -v140
	v_fmac_f32_e32 v47, 0x3377d1cf, v41
	v_fmac_f32_e32 v140, 0x3377d1cf, v42
	v_fmac_f32_e32 v47, 0x3f317217, v41
	v_fmac_f32_e32 v140, 0x3f317217, v42
	v_cmp_lt_f32_e64 s[30:31], |v41|, s63
	v_cmp_lt_f32_e64 s[34:35], |v42|, s63
	s_nop 1
	v_cndmask_b32_e64 v41, v41, v47, s[30:31]
	v_cndmask_b32_e64 v42, v42, v140, s[34:35]
	v_sub_f32_e32 v41, v41, v45
	v_sub_f32_e32 v42, v42, v46
	v_sub_f32_e32 v41, v43, v41
	v_sub_f32_e32 v42, v44, v42
	v_fma_f32 v219, v41, s2, v218
	v_fma_f32 v220, v42, s2, v219
	s_waitcnt lgkmcnt(0)
	v_mov_b32_e32 v141, v38
	v_mov_b32_e32 v142, v38
	v_fmac_f32_e32 v141, v172, v201
	v_fmac_f32_e32 v142, v228, v201
	v_fmac_f32_e32 v141, v173, v202
	v_fmac_f32_e32 v142, v229, v202
	v_fmac_f32_e32 v141, v174, v203
	v_fmac_f32_e32 v142, v230, v203
	v_fmac_f32_e32 v141, v175, v204
	v_fmac_f32_e32 v142, v231, v204
	v_fmac_f32_e32 v141, v176, v205
	v_fmac_f32_e32 v142, v232, v205
	v_fmac_f32_e32 v141, v177, v206
	v_fmac_f32_e32 v142, v233, v206
	v_fmac_f32_e32 v141, v178, v207
	v_fmac_f32_e32 v142, v234, v207
	v_fmac_f32_e32 v141, v179, v208
	v_fmac_f32_e32 v142, v235, v208
	v_fmac_f32_e32 v141, v180, v209
	v_fmac_f32_e32 v142, v236, v209
	v_fmac_f32_e32 v141, v181, v210
	v_fmac_f32_e32 v142, v237, v210
	v_fmac_f32_e32 v141, v182, v211
	v_fmac_f32_e32 v142, v238, v211
	v_fmac_f32_e32 v141, v183, v212
	v_fmac_f32_e32 v142, v239, v212
	v_fmac_f32_e32 v141, v164, v213
	v_fmac_f32_e32 v142, v240, v213
	v_fmac_f32_e32 v141, v165, v214
	v_fmac_f32_e32 v142, v241, v214
	v_fmac_f32_e32 v141, v166, v215
	v_fmac_f32_e32 v142, v242, v215
	v_fmac_f32_e32 v141, v167, v216
	v_fmac_f32_e32 v142, v243, v216
	v_add_u32_e32 v143, s100, v143
	v_add_u32_e32 v144, s100, v144
	ds_read_b128 v[172:175], v143
	ds_read_b128 v[176:179], v143 offset:16
	ds_read_b128 v[180:183], v143 offset:32
	ds_read_b128 v[164:167], v143 offset:48
	ds_read_b128 v[228:231], v144
	ds_read_b128 v[232:235], v144 offset:16
	ds_read_b128 v[236:239], v144 offset:32
	ds_read_b128 v[240:243], v144 offset:48
	v_mul_f32_e64 v41, |v141|, s61
	v_mul_f32_e64 v42, |v142|, s61
	v_exp_f32_e32 v41, v41
	v_exp_f32_e32 v42, v42
	v_min_f32_e32 v43, 0, v141
	v_min_f32_e32 v44, 0, v142
	v_add_f32_e32 v41, 1.0, v41
	v_add_f32_e32 v42, 1.0, v42
	v_cmp_gt_f32_e64 s[4:5], s24, v41
	v_cmp_gt_f32_e64 s[6:7], s24, v42
	s_nop 1
	v_cndmask_b32_e64 v45, 0, 32, s[4:5]
	v_cndmask_b32_e64 v46, 0, 32, s[6:7]
	v_ldexp_f32 v41, v41, v45
	v_ldexp_f32 v42, v42, v46
	v_log_f32_e32 v41, v41
	v_log_f32_e32 v42, v42
	v_cndmask_b32_e64 v45, 0, v192, s[4:5]
	v_cndmask_b32_e64 v46, 0, v192, s[6:7]
	v_mul_f32_e32 v47, 0x3f317217, v41
	v_mul_f32_e32 v140, 0x3f317217, v42
	v_fma_f32 v47, v41, s62, -v47
	v_fma_f32 v140, v42, s62, -v140
	v_fmac_f32_e32 v47, 0x3377d1cf, v41
	v_fmac_f32_e32 v140, 0x3377d1cf, v42
	v_fmac_f32_e32 v47, 0x3f317217, v41
	v_fmac_f32_e32 v140, 0x3f317217, v42
	v_cmp_lt_f32_e64 s[30:31], |v41|, s63
	v_cmp_lt_f32_e64 s[34:35], |v42|, s63
	s_nop 1
	v_cndmask_b32_e64 v41, v41, v47, s[30:31]
	v_cndmask_b32_e64 v42, v42, v140, s[34:35]
	v_sub_f32_e32 v41, v41, v45
	v_sub_f32_e32 v42, v42, v46
	v_sub_f32_e32 v41, v43, v41
	v_sub_f32_e32 v42, v44, v42
	v_fma_f32 v221, v41, s2, v220
	v_fma_f32 v222, v42, s2, v221
	s_waitcnt lgkmcnt(0)
; __device__ __forceinline__ void gla_b(const Args& a, int l, int hd, int dir, int t0, unsigned char* sm, const bf16_t* __restrict__ PLR) {
;     ...
;     for (int k = 0; k < 16; ++k) {
;         const int s = q * 16 + k, j = dir ? 63 - s : s;
;         float x = Bs[d];
; #pragma unroll
;         for (int r = 0; r < 16; ++r) x += lrs[j * 16 + r] * W2s[r * 128 + d];
;         const float g = (fminf(x, 0.f) - __logf(1.f + __expf(-fabsf(x)))) * (1.f / 16.f);
;         run += g; Gb[j * 129 + d] = run;
;     }
	v_mov_b32_e32 v141, v38
	v_mov_b32_e32 v142, v38
	v_fmac_f32_e32 v141, v172, v201
	v_fmac_f32_e32 v142, v228, v201
	v_fmac_f32_e32 v141, v173, v202
	v_fmac_f32_e32 v142, v229, v202
	v_fmac_f32_e32 v141, v174, v203
	v_fmac_f32_e32 v142, v230, v203
	v_fmac_f32_e32 v141, v175, v204
	v_fmac_f32_e32 v142, v231, v204
	v_fmac_f32_e32 v141, v176, v205
	v_fmac_f32_e32 v142, v232, v205
	v_fmac_f32_e32 v141, v177, v206
	v_fmac_f32_e32 v142, v233, v206
	v_fmac_f32_e32 v141, v178, v207
	v_fmac_f32_e32 v142, v234, v207
	v_fmac_f32_e32 v141, v179, v208
	v_fmac_f32_e32 v142, v235, v208
	v_fmac_f32_e32 v141, v180, v209
	v_fmac_f32_e32 v142, v236, v209
	v_fmac_f32_e32 v141, v181, v210
	v_fmac_f32_e32 v142, v237, v210
	v_fmac_f32_e32 v141, v182, v211
	v_fmac_f32_e32 v142, v238, v211
	v_fmac_f32_e32 v141, v183, v212
	v_fmac_f32_e32 v142, v239, v212
	v_fmac_f32_e32 v141, v164, v213
	v_fmac_f32_e32 v142, v240, v213
	v_fmac_f32_e32 v141, v165, v214
	v_fmac_f32_e32 v142, v241, v214
	v_fmac_f32_e32 v141, v166, v215
	v_fmac_f32_e32 v142, v242, v215
	v_fmac_f32_e32 v141, v167, v216
	v_fmac_f32_e32 v142, v243, v216
	v_add_u32_e32 v143, s100, v143
	v_add_u32_e32 v144, s100, v144
	ds_read_b128 v[172:175], v143
	ds_read_b128 v[176:179], v143 offset:16
	ds_read_b128 v[180:183], v143 offset:32
	ds_read_b128 v[164:167], v143 offset:48
	ds_read_b128 v[228:231], v144
	ds_read_b128 v[232:235], v144 offset:16
	ds_read_b128 v[236:239], v144 offset:32
	ds_read_b128 v[240:243], v144 offset:48
	v_mul_f32_e64 v41, |v141|, s61
	v_mul_f32_e64 v42, |v142|, s61
	v_exp_f32_e32 v41, v41
	v_exp_f32_e32 v42, v42
	v_min_f32_e32 v43, 0, v141
	v_min_f32_e32 v44, 0, v142
	v_add_f32_e32 v41, 1.0, v41
	v_add_f32_e32 v42, 1.0, v42
	v_cmp_gt_f32_e64 s[4:5], s24, v41
	v_cmp_gt_f32_e64 s[6:7], s24, v42
	s_nop 1
	v_cndmask_b32_e64 v45, 0, 32, s[4:5]
	v_cndmask_b32_e64 v46, 0, 32, s[6:7]
	v_ldexp_f32 v41, v41, v45
	v_ldexp_f32 v42, v42, v46
	v_log_f32_e32 v41, v41
	v_log_f32_e32 v42, v42
	v_cndmask_b32_e64 v45, 0, v192, s[4:5]
	v_cndmask_b32_e64 v46, 0, v192, s[6:7]
	v_mul_f32_e32 v47, 0x3f317217, v41
	v_mul_f32_e32 v140, 0x3f317217, v42
	v_fma_f32 v47, v41, s62, -v47
	v_fma_f32 v140, v42, s62, -v140
	v_fmac_f32_e32 v47, 0x3377d1cf, v41
	v_fmac_f32_e32 v140, 0x3377d1cf, v42
	v_fmac_f32_e32 v47, 0x3f317217, v41
	v_fmac_f32_e32 v140, 0x3f317217, v42
	v_cmp_lt_f32_e64 s[30:31], |v41|, s63
	v_cmp_lt_f32_e64 s[34:35], |v42|, s63
	s_nop 1
	v_cndmask_b32_e64 v41, v41, v47, s[30:31]
	v_cndmask_b32_e64 v42, v42, v140, s[34:35]
	v_sub_f32_e32 v41, v41, v45
	v_sub_f32_e32 v42, v42, v46
	v_sub_f32_e32 v41, v43, v41
	v_sub_f32_e32 v42, v44, v42
	v_fma_f32 v223, v41, s2, v222
	v_fma_f32 v224, v42, s2, v223
	s_waitcnt lgkmcnt(0)
	v_mov_b32_e32 v141, v38
	v_mov_b32_e32 v142, v38
	v_fmac_f32_e32 v141, v172, v201
	v_fmac_f32_e32 v142, v228, v201
	v_fmac_f32_e32 v141, v173, v202
	v_fmac_f32_e32 v142, v229, v202
	v_fmac_f32_e32 v141, v174, v203
	v_fmac_f32_e32 v142, v230, v203
	v_fmac_f32_e32 v141, v175, v204
	v_fmac_f32_e32 v142, v231, v204
	v_fmac_f32_e32 v141, v176, v205
	v_fmac_f32_e32 v142, v232, v205
	v_fmac_f32_e32 v141, v177, v206
	v_fmac_f32_e32 v142, v233, v206
	v_fmac_f32_e32 v141, v178, v207
	v_fmac_f32_e32 v142, v234, v207
	v_fmac_f32_e32 v141, v179, v208
	v_fmac_f32_e32 v142, v235, v208
	v_fmac_f32_e32 v141, v180, v209
	v_fmac_f32_e32 v142, v236, v209
	v_fmac_f32_e32 v141, v181, v210
	v_fmac_f32_e32 v142, v237, v210
	v_fmac_f32_e32 v141, v182, v211
	v_fmac_f32_e32 v142, v238, v211
	v_fmac_f32_e32 v141, v183, v212
	v_fmac_f32_e32 v142, v239, v212
	v_fmac_f32_e32 v141, v164, v213
	v_fmac_f32_e32 v142, v240, v213
	v_fmac_f32_e32 v141, v165, v214
	v_fmac_f32_e32 v142, v241, v214
	v_fmac_f32_e32 v141, v166, v215
	v_fmac_f32_e32 v142, v242, v215
	v_fmac_f32_e32 v141, v167, v216
	v_fmac_f32_e32 v142, v243, v216
	v_add_u32_e32 v143, s100, v143
	v_add_u32_e32 v144, s100, v144
	ds_read_b128 v[172:175], v143
	ds_read_b128 v[176:179], v143 offset:16
	ds_read_b128 v[180:183], v143 offset:32
	ds_read_b128 v[164:167], v143 offset:48
	ds_read_b128 v[228:231], v144
	ds_read_b128 v[232:235], v144 offset:16
	ds_read_b128 v[236:239], v144 offset:32
	ds_read_b128 v[240:243], v144 offset:48
	v_mul_f32_e64 v41, |v141|, s61
	v_mul_f32_e64 v42, |v142|, s61
	v_exp_f32_e32 v41, v41
	v_exp_f32_e32 v42, v42
	v_min_f32_e32 v43, 0, v141
	v_min_f32_e32 v44, 0, v142
	v_add_f32_e32 v41, 1.0, v41
	v_add_f32_e32 v42, 1.0, v42
	v_cmp_gt_f32_e64 s[4:5], s24, v41
	v_cmp_gt_f32_e64 s[6:7], s24, v42
	s_nop 1
	v_cndmask_b32_e64 v45, 0, 32, s[4:5]
	v_cndmask_b32_e64 v46, 0, 32, s[6:7]
	v_ldexp_f32 v41, v41, v45
	v_ldexp_f32 v42, v42, v46
	v_log_f32_e32 v41, v41
	v_log_f32_e32 v42, v42
	v_cndmask_b32_e64 v45, 0, v192, s[4:5]
	v_cndmask_b32_e64 v46, 0, v192, s[6:7]
	v_mul_f32_e32 v47, 0x3f317217, v41
	v_mul_f32_e32 v140, 0x3f317217, v42
	v_fma_f32 v47, v41, s62, -v47
	v_fma_f32 v140, v42, s62, -v140
	v_fmac_f32_e32 v47, 0x3377d1cf, v41
	v_fmac_f32_e32 v140, 0x3377d1cf, v42
	v_fmac_f32_e32 v47, 0x3f317217, v41
	v_fmac_f32_e32 v140, 0x3f317217, v42
	v_cmp_lt_f32_e64 s[30:31], |v41|, s63
	v_cmp_lt_f32_e64 s[34:35], |v42|, s63
	s_nop 1
	v_cndmask_b32_e64 v41, v41, v47, s[30:31]
	v_cndmask_b32_e64 v42, v42, v140, s[34:35]
	v_sub_f32_e32 v41, v41, v45
	v_sub_f32_e32 v42, v42, v46
	v_sub_f32_e32 v41, v43, v41
	v_sub_f32_e32 v42, v44, v42
	v_fma_f32 v225, v41, s2, v224
	v_fma_f32 v226, v42, s2, v225
	s_waitcnt lgkmcnt(0)
; __device__ __forceinline__ void gla_b(const Args& a, int l, int hd, int dir, int t0, unsigned char* sm, const bf16_t* __restrict__ PLR) {
;     ...
;     for (int k = 0; k < 16; ++k) {
;         const int s = q * 16 + k, j = dir ? 63 - s : s;
;         float x = Bs[d];
; #pragma unroll
;         for (int r = 0; r < 16; ++r) x += lrs[j * 16 + r] * W2s[r * 128 + d];
;         const float g = (fminf(x, 0.f) - __logf(1.f + __expf(-fabsf(x)))) * (1.f / 16.f);
;         run += g; Gb[j * 129 + d] = run;
;     }
	v_mov_b32_e32 v141, v38
	v_mov_b32_e32 v142, v38
	v_fmac_f32_e32 v141, v172, v201
	v_fmac_f32_e32 v142, v228, v201
	v_fmac_f32_e32 v141, v173, v202
	v_fmac_f32_e32 v142, v229, v202
	v_fmac_f32_e32 v141, v174, v203
	v_fmac_f32_e32 v142, v230, v203
	v_fmac_f32_e32 v141, v175, v204
	v_fmac_f32_e32 v142, v231, v204
	v_fmac_f32_e32 v141, v176, v205
	v_fmac_f32_e32 v142, v232, v205
	v_fmac_f32_e32 v141, v177, v206
	v_fmac_f32_e32 v142, v233, v206
	v_fmac_f32_e32 v141, v178, v207
	v_fmac_f32_e32 v142, v234, v207
	v_fmac_f32_e32 v141, v179, v208
	v_fmac_f32_e32 v142, v235, v208
	v_fmac_f32_e32 v141, v180, v209
	v_fmac_f32_e32 v142, v236, v209
	v_fmac_f32_e32 v141, v181, v210
	v_fmac_f32_e32 v142, v237, v210
	v_fmac_f32_e32 v141, v182, v211
	v_fmac_f32_e32 v142, v238, v211
	v_fmac_f32_e32 v141, v183, v212
	v_fmac_f32_e32 v142, v239, v212
	v_fmac_f32_e32 v141, v164, v213
	v_fmac_f32_e32 v142, v240, v213
	v_fmac_f32_e32 v141, v165, v214
	v_fmac_f32_e32 v142, v241, v214
	v_fmac_f32_e32 v141, v166, v215
	v_fmac_f32_e32 v142, v242, v215
	v_fmac_f32_e32 v141, v167, v216
	v_fmac_f32_e32 v142, v243, v216
	v_add_u32_e32 v143, s100, v143
	v_add_u32_e32 v144, s100, v144
	ds_read_b128 v[172:175], v143
	ds_read_b128 v[176:179], v143 offset:16
	ds_read_b128 v[180:183], v143 offset:32
	ds_read_b128 v[164:167], v143 offset:48
	ds_read_b128 v[228:231], v144
	ds_read_b128 v[232:235], v144 offset:16
	ds_read_b128 v[236:239], v144 offset:32
	ds_read_b128 v[240:243], v144 offset:48
	v_mul_f32_e64 v41, |v141|, s61
	v_mul_f32_e64 v42, |v142|, s61
	v_exp_f32_e32 v41, v41
	v_exp_f32_e32 v42, v42
	v_min_f32_e32 v43, 0, v141
	v_min_f32_e32 v44, 0, v142
	v_add_f32_e32 v41, 1.0, v41
	v_add_f32_e32 v42, 1.0, v42
	v_cmp_gt_f32_e64 s[4:5], s24, v41
	v_cmp_gt_f32_e64 s[6:7], s24, v42
	s_nop 1
	v_cndmask_b32_e64 v45, 0, 32, s[4:5]
	v_cndmask_b32_e64 v46, 0, 32, s[6:7]
	v_ldexp_f32 v41, v41, v45
	v_ldexp_f32 v42, v42, v46
	v_log_f32_e32 v41, v41
	v_log_f32_e32 v42, v42
	v_cndmask_b32_e64 v45, 0, v192, s[4:5]
	v_cndmask_b32_e64 v46, 0, v192, s[6:7]
	v_mul_f32_e32 v47, 0x3f317217, v41
	v_mul_f32_e32 v140, 0x3f317217, v42
	v_fma_f32 v47, v41, s62, -v47
	v_fma_f32 v140, v42, s62, -v140
	v_fmac_f32_e32 v47, 0x3377d1cf, v41
	v_fmac_f32_e32 v140, 0x3377d1cf, v42
	v_fmac_f32_e32 v47, 0x3f317217, v41
	v_fmac_f32_e32 v140, 0x3f317217, v42
	v_cmp_lt_f32_e64 s[30:31], |v41|, s63
	v_cmp_lt_f32_e64 s[34:35], |v42|, s63
	s_nop 1
	v_cndmask_b32_e64 v41, v41, v47, s[30:31]
	v_cndmask_b32_e64 v42, v42, v140, s[34:35]
	v_sub_f32_e32 v41, v41, v45
	v_sub_f32_e32 v42, v42, v46
	v_sub_f32_e32 v41, v43, v41
	v_sub_f32_e32 v42, v44, v42
	v_fma_f32 v227, v41, s2, v226
	v_fma_f32 v184, v42, s2, v227
	s_waitcnt lgkmcnt(0)
	v_mov_b32_e32 v141, v38
	v_mov_b32_e32 v142, v38
	v_fmac_f32_e32 v141, v172, v201
	v_fmac_f32_e32 v142, v228, v201
	v_fmac_f32_e32 v141, v173, v202
	v_fmac_f32_e32 v142, v229, v202
	v_fmac_f32_e32 v141, v174, v203
	v_fmac_f32_e32 v142, v230, v203
	v_fmac_f32_e32 v141, v175, v204
	v_fmac_f32_e32 v142, v231, v204
	v_fmac_f32_e32 v141, v176, v205
	v_fmac_f32_e32 v142, v232, v205
	v_fmac_f32_e32 v141, v177, v206
	v_fmac_f32_e32 v142, v233, v206
	v_fmac_f32_e32 v141, v178, v207
	v_fmac_f32_e32 v142, v234, v207
	v_fmac_f32_e32 v141, v179, v208
	v_fmac_f32_e32 v142, v235, v208
	v_fmac_f32_e32 v141, v180, v209
	v_fmac_f32_e32 v142, v236, v209
	v_fmac_f32_e32 v141, v181, v210
	v_fmac_f32_e32 v142, v237, v210
	v_fmac_f32_e32 v141, v182, v211
	v_fmac_f32_e32 v142, v238, v211
	v_fmac_f32_e32 v141, v183, v212
	v_fmac_f32_e32 v142, v239, v212
	v_fmac_f32_e32 v141, v164, v213
	v_fmac_f32_e32 v142, v240, v213
	v_fmac_f32_e32 v141, v165, v214
	v_fmac_f32_e32 v142, v241, v214
	v_fmac_f32_e32 v141, v166, v215
	v_fmac_f32_e32 v142, v242, v215
	v_fmac_f32_e32 v141, v167, v216
	v_fmac_f32_e32 v142, v243, v216
	v_add_u32_e32 v143, s100, v143
	v_add_u32_e32 v144, s100, v144
	ds_read_b128 v[172:175], v143
	ds_read_b128 v[176:179], v143 offset:16
	ds_read_b128 v[180:183], v143 offset:32
	ds_read_b128 v[164:167], v143 offset:48
	ds_read_b128 v[228:231], v144
	ds_read_b128 v[232:235], v144 offset:16
	ds_read_b128 v[236:239], v144 offset:32
	ds_read_b128 v[240:243], v144 offset:48
	v_mul_f32_e64 v41, |v141|, s61
	v_mul_f32_e64 v42, |v142|, s61
	v_exp_f32_e32 v41, v41
	v_exp_f32_e32 v42, v42
	v_min_f32_e32 v43, 0, v141
	v_min_f32_e32 v44, 0, v142
	v_add_f32_e32 v41, 1.0, v41
	v_add_f32_e32 v42, 1.0, v42
	v_cmp_gt_f32_e64 s[4:5], s24, v41
	v_cmp_gt_f32_e64 s[6:7], s24, v42
	s_nop 1
	v_cndmask_b32_e64 v45, 0, 32, s[4:5]
	v_cndmask_b32_e64 v46, 0, 32, s[6:7]
	v_ldexp_f32 v41, v41, v45
	v_ldexp_f32 v42, v42, v46
	v_log_f32_e32 v41, v41
	v_log_f32_e32 v42, v42
	v_cndmask_b32_e64 v45, 0, v192, s[4:5]
	v_cndmask_b32_e64 v46, 0, v192, s[6:7]
	v_mul_f32_e32 v47, 0x3f317217, v41
	v_mul_f32_e32 v140, 0x3f317217, v42
	v_fma_f32 v47, v41, s62, -v47
	v_fma_f32 v140, v42, s62, -v140
	v_fmac_f32_e32 v47, 0x3377d1cf, v41
	v_fmac_f32_e32 v140, 0x3377d1cf, v42
	v_fmac_f32_e32 v47, 0x3f317217, v41
	v_fmac_f32_e32 v140, 0x3f317217, v42
	v_cmp_lt_f32_e64 s[30:31], |v41|, s63
	v_cmp_lt_f32_e64 s[34:35], |v42|, s63
	s_nop 1
	v_cndmask_b32_e64 v41, v41, v47, s[30:31]
	v_cndmask_b32_e64 v42, v42, v140, s[34:35]
	v_sub_f32_e32 v41, v41, v45
	v_sub_f32_e32 v42, v42, v46
	v_sub_f32_e32 v41, v43, v41
	v_sub_f32_e32 v42, v44, v42
	v_fma_f32 v185, v41, s2, v184
	v_fma_f32 v162, v42, s2, v185
	s_waitcnt lgkmcnt(0)
; __device__ __forceinline__ void gla_b(const Args& a, int l, int hd, int dir, int t0, unsigned char* sm, const bf16_t* __restrict__ PLR) {
;     ...
;     for (int k = 0; k < 16; ++k) {
;         const int s = q * 16 + k, j = dir ? 63 - s : s;
;         float x = Bs[d];
; #pragma unroll
;         for (int r = 0; r < 16; ++r) x += lrs[j * 16 + r] * W2s[r * 128 + d];
;         const float g = (fminf(x, 0.f) - __logf(1.f + __expf(-fabsf(x)))) * (1.f / 16.f);
;         run += g; Gb[j * 129 + d] = run;
;     }
;     tot[q * 128 + d] = run;
;     __syncthreads();
;     float off = 0.f;
;     for (int qq = 0; qq < q; ++qq) off += tot[qq * 128 + d];
;     if (q > 0) for (int k = 0; k < 16; ++k) { const int s = q * 16 + k, j = dir ? 63 - s : s; Gb[j * 129 + d] += off; }
;     __syncthreads();
	v_mov_b32_e32 v141, v38
	v_mov_b32_e32 v142, v38
	v_fmac_f32_e32 v141, v172, v201
	v_fmac_f32_e32 v142, v228, v201
	v_fmac_f32_e32 v141, v173, v202
	v_fmac_f32_e32 v142, v229, v202
	v_fmac_f32_e32 v141, v174, v203
	v_fmac_f32_e32 v142, v230, v203
	v_fmac_f32_e32 v141, v175, v204
	v_fmac_f32_e32 v142, v231, v204
	v_fmac_f32_e32 v141, v176, v205
	v_fmac_f32_e32 v142, v232, v205
	v_fmac_f32_e32 v141, v177, v206
	v_fmac_f32_e32 v142, v233, v206
	v_fmac_f32_e32 v141, v178, v207
	v_fmac_f32_e32 v142, v234, v207
	v_fmac_f32_e32 v141, v179, v208
	v_fmac_f32_e32 v142, v235, v208
	v_fmac_f32_e32 v141, v180, v209
	v_fmac_f32_e32 v142, v236, v209
	v_fmac_f32_e32 v141, v181, v210
	v_fmac_f32_e32 v142, v237, v210
	v_fmac_f32_e32 v141, v182, v211
	v_fmac_f32_e32 v142, v238, v211
	v_fmac_f32_e32 v141, v183, v212
	v_fmac_f32_e32 v142, v239, v212
	v_fmac_f32_e32 v141, v164, v213
	v_fmac_f32_e32 v142, v240, v213
	v_fmac_f32_e32 v141, v165, v214
	v_fmac_f32_e32 v142, v241, v214
	v_fmac_f32_e32 v141, v166, v215
	v_fmac_f32_e32 v142, v242, v215
	v_fmac_f32_e32 v141, v167, v216
	v_fmac_f32_e32 v142, v243, v216
	v_mul_f32_e64 v41, |v141|, s61
	v_mul_f32_e64 v42, |v142|, s61
	v_exp_f32_e32 v41, v41
	v_exp_f32_e32 v42, v42
	v_min_f32_e32 v43, 0, v141
	v_min_f32_e32 v44, 0, v142
	v_add_f32_e32 v41, 1.0, v41
	v_add_f32_e32 v42, 1.0, v42
	v_cmp_gt_f32_e64 s[4:5], s24, v41
	v_cmp_gt_f32_e64 s[6:7], s24, v42
	s_nop 1
	v_cndmask_b32_e64 v45, 0, 32, s[4:5]
	v_cndmask_b32_e64 v46, 0, 32, s[6:7]
	v_ldexp_f32 v41, v41, v45
	v_ldexp_f32 v42, v42, v46
	v_log_f32_e32 v41, v41
	v_log_f32_e32 v42, v42
	v_cndmask_b32_e64 v45, 0, v192, s[4:5]
	v_cndmask_b32_e64 v46, 0, v192, s[6:7]
	v_mul_f32_e32 v47, 0x3f317217, v41
	v_mul_f32_e32 v140, 0x3f317217, v42
	v_fma_f32 v47, v41, s62, -v47
	v_fma_f32 v140, v42, s62, -v140
	v_fmac_f32_e32 v47, 0x3377d1cf, v41
	v_fmac_f32_e32 v140, 0x3377d1cf, v42
	v_fmac_f32_e32 v47, 0x3f317217, v41
	v_fmac_f32_e32 v140, 0x3f317217, v42
	v_cmp_lt_f32_e64 s[30:31], |v41|, s63
	v_cmp_lt_f32_e64 s[34:35], |v42|, s63
	s_nop 1
	v_cndmask_b32_e64 v41, v41, v47, s[30:31]
	v_cndmask_b32_e64 v42, v42, v140, s[34:35]
	v_sub_f32_e32 v41, v41, v45
	v_sub_f32_e32 v42, v42, v46
	v_sub_f32_e32 v41, v43, v41
	v_sub_f32_e32 v42, v44, v42
	v_fma_f32 v163, v41, s2, v162
	v_fma_f32 v168, v42, s2, v163
	ds_write_b32 v33, v168 offset:45824
	s_waitcnt lgkmcnt(0)
	s_barrier
	ds_read_b32 v41, v32 offset:45824
	ds_read_b32 v42, v32 offset:46336
	ds_read_b32 v43, v32 offset:46848
	v_lshrrev_b32_e32 v39, 7, v171
	v_cmp_lt_u32_e64 s[4:5], 0, v39
	v_cmp_lt_u32_e64 s[6:7], 1, v39
	v_cmp_lt_u32_e64 s[30:31], 2, v39
	s_waitcnt lgkmcnt(0)
	v_cndmask_b32_e64 v41, 0, v41, s[4:5]
	v_cndmask_b32_e64 v42, 0, v42, s[6:7]
	v_cndmask_b32_e64 v43, 0, v43, s[30:31]
	v_add_f32_e32 v41, v41, v42
	v_add_f32_e32 v41, v41, v43
	v_add_f32_e32 v45, v217, v41
	ds_write_b32 v40, v45
	v_add_u32_e32 v40, s101, v40
	v_add_f32_e32 v46, v218, v41
	ds_write_b32 v40, v46
	v_add_u32_e32 v40, s101, v40
	v_add_f32_e32 v45, v219, v41
	ds_write_b32 v40, v45
	v_add_u32_e32 v40, s101, v40
	v_add_f32_e32 v46, v220, v41
	ds_write_b32 v40, v46
	v_add_u32_e32 v40, s101, v40
	v_add_f32_e32 v45, v221, v41
	ds_write_b32 v40, v45
	v_add_u32_e32 v40, s101, v40
	v_add_f32_e32 v46, v222, v41
	ds_write_b32 v40, v46
	v_add_u32_e32 v40, s101, v40
	v_add_f32_e32 v45, v223, v41
	ds_write_b32 v40, v45
	v_add_u32_e32 v40, s101, v40
	v_add_f32_e32 v46, v224, v41
	ds_write_b32 v40, v46
	v_add_u32_e32 v40, s101, v40
	v_add_f32_e32 v45, v225, v41
	ds_write_b32 v40, v45
	v_add_u32_e32 v40, s101, v40
	v_add_f32_e32 v46, v226, v41
	ds_write_b32 v40, v46
	v_add_u32_e32 v40, s101, v40
	v_add_f32_e32 v45, v227, v41
	ds_write_b32 v40, v45
	v_add_u32_e32 v40, s101, v40
	v_add_f32_e32 v46, v184, v41
	ds_write_b32 v40, v46
	v_add_u32_e32 v40, s101, v40
	v_add_f32_e32 v45, v185, v41
	ds_write_b32 v40, v45
	v_add_u32_e32 v40, s101, v40
	v_add_f32_e32 v46, v162, v41
	ds_write_b32 v40, v46
	v_add_u32_e32 v40, s101, v40
	v_add_f32_e32 v45, v163, v41
	ds_write_b32 v40, v45
	v_add_u32_e32 v40, s101, v40
	v_add_f32_e32 v46, v168, v41
	ds_write_b32 v40, v46
	s_mov_b64 s[4:5], exec

; __global__ void __launch_bounds__(512, 2) mega(Args a) {
	.amdhsa_kernel _Z4mega4Args
		.amdhsa_group_segment_fixed_size 0
		.amdhsa_private_segment_fixed_size 0
		.amdhsa_kernarg_size 512
		.amdhsa_user_sgpr_count 2
		.amdhsa_user_sgpr_dispatch_ptr 0
		.amdhsa_user_sgpr_queue_ptr 0
		.amdhsa_user_sgpr_kernarg_segment_ptr 1
		.amdhsa_user_sgpr_dispatch_id 0
		.amdhsa_user_sgpr_kernarg_preload_length 0
		.amdhsa_user_sgpr_kernarg_preload_offset 0
		.amdhsa_user_sgpr_private_segment_size 0
		.amdhsa_uses_dynamic_stack 0
		.amdhsa_enable_private_segment 0
		.amdhsa_system_sgpr_workgroup_id_x 1
		.amdhsa_system_sgpr_workgroup_id_y 0
		.amdhsa_system_sgpr_workgroup_id_z 0
		.amdhsa_system_sgpr_workgroup_info 0
		.amdhsa_system_vgpr_workitem_id 2
		.amdhsa_next_free_vgpr 250
		.amdhsa_next_free_sgpr 102
		.amdhsa_accum_offset 252
		.amdhsa_reserve_vcc 1
		.amdhsa_float_round_mode_32 0
		.amdhsa_float_round_mode_16_64 0
		.amdhsa_float_denorm_mode_32 3
		.amdhsa_float_denorm_mode_16_64 3
		.amdhsa_dx10_clamp 1
		.amdhsa_ieee_mode 1
		.amdhsa_fp16_overflow 0
		.amdhsa_tg_split 0
		.amdhsa_exception_fp_ieee_invalid_op 0
		.amdhsa_exception_fp_denorm_src 0
		.amdhsa_exception_fp_ieee_div_zero 0
		.amdhsa_exception_fp_ieee_overflow 0
		.amdhsa_exception_fp_ieee_underflow 0
		.amdhsa_exception_fp_ieee_inexact 0
		.amdhsa_exception_int_div_zero 0
	.end_amdhsa_kernel

; __global__ void __launch_bounds__(512, 2) mega(Args a) {
amdhsa.kernels:
  - .agpr_count:     0
    .args:
      - .offset:         0
        .size:           256
        .value_kind:     by_value
      - .offset:         256
        .size:           4
        .value_kind:     hidden_block_count_x
      - .offset:         260
        .size:           4
        .value_kind:     hidden_block_count_y
      - .offset:         264
        .size:           4
        .value_kind:     hidden_block_count_z
      - .offset:         268
        .size:           2
        .value_kind:     hidden_group_size_x
      - .offset:         270
        .size:           2
        .value_kind:     hidden_group_size_y
      - .offset:         272
        .size:           2
        .value_kind:     hidden_group_size_z
      - .offset:         274
        .size:           2
        .value_kind:     hidden_remainder_x
      - .offset:         276
        .size:           2
        .value_kind:     hidden_remainder_y
      - .offset:         278
        .size:           2
        .value_kind:     hidden_remainder_z
      - .offset:         296
        .size:           8
        .value_kind:     hidden_global_offset_x
      - .offset:         304
        .size:           8
        .value_kind:     hidden_global_offset_y
      - .offset:         312
        .size:           8
        .value_kind:     hidden_global_offset_z
      - .offset:         320
        .size:           2
        .value_kind:     hidden_grid_dims
      - .offset:         344
        .size:           8
        .value_kind:     hidden_multigrid_sync_arg
      - .offset:         376
        .size:           4
        .value_kind:     hidden_dynamic_lds_size
    .group_segment_fixed_size: 0
    .kernarg_segment_align: 8
    .kernarg_segment_size: 512
    .language:       OpenCL C
    .language_version:
      - 2
      - 0
    .max_flat_workgroup_size: 512
    .name:           _Z4mega4Args
    .private_segment_fixed_size: 0
    .sgpr_count:     108
    .sgpr_spill_count: 377
    .symbol:         _Z4mega4Args.kd
    .uniform_work_group_size: 1
    .uses_dynamic_stack: false
    .vgpr_count:     250
    .vgpr_spill_count: 0
    .wavefront_size: 64
